# G3 epilogue: all eight sum-of-squares row loads issued in one batch (one exposed round trip instead of two)
# baseline (speedup 1.0000x reference)
; __device__ __forceinline__ float bperm_f(int src_lane, float v) { return __builtin_bit_cast(float, __builtin_amdgcn_ds_bpermute(src_lane << 2, __builtin_bit_cast(int, v))); }
;     __device__ __forceinline__ void operator()(Acc& acc, const Unit& u, int wr, int wc, int fr, int fq) const {
;         const int b = u.pm / UPU, j = u.pm % UPU;
;         const int tbase = 252 * j + 126 * wr - 2 + fr;
;         const int ch0 = 128 * u.pn + 32 * wc + 8 * fq;
;         float chain = 0.f;
;         { const int ln = (fq << 4) | fr; f32x4 pq[8];
; #pragma unroll
;           for (int q = 0; q < 8; ++q) { const int t = tbase + 16 * q; const bool ok = (t >= 0) && (t < SEQ); pq[q] = *(const f32x4*)(ssq + (size_t)(b * SEQ + (ok ? t : 0)) * 16 + 4 * fq); }
; #pragma unroll
;           for (int q = 0; q < 8; ++q) {
;             const int t = tbase + 16 * q; const bool ok = (t >= 0) && (t < SEQ);
;             float sq = (pq[q][0] + pq[q][1]) + (pq[q][2] + pq[q][3]); sq += bperm_f(ln ^ 16, sq); sq += bperm_f(ln ^ 32, sq);
;             const float rs = rsqrtf(sq * (1.0f / DM) + EPS);
; #pragma unroll
;             for (int bj = 0; bj < 2; ++bj)
; #pragma unroll
;                 for (int n = 0; n < 2; ++n)
; #pragma unroll
;                     for (int i = 0; i < 4; ++i) { const float v = acc[q >> 2][bj][q & 3][n][i]; acc[q >> 2][bj][q & 3][n][i] = ok ? v * rs : 0.f; }
.LBB0_43:
	s_mul_hi_i32 s21, s20, 0x3e0f83e1
	s_lshr_b32 s27, s21, 31
	s_ashr_i32 s21, s21, 3
	s_add_i32 s21, s21, s27
	s_mul_i32 s27, s21, 33
	s_sub_i32 s20, s20, s27
	s_mulk_i32 s20, 0xfc
	v_add_u32_e32 v198, s20, v194
	v_add_u32_e32 v223, 16, v198
	v_cmp_gt_u32_e64 s[56:57], s97, v198
	v_cmp_gt_u32_e64 s[52:53], s97, v223
	s_lshl_b32 s20, s21, 13
	v_cndmask_b32_e64 v132, 0, v198, s[56:57]
	v_cndmask_b32_e64 v136, 0, v223, s[52:53]
	v_add_u32_e32 v132, s20, v132
	v_add_u32_e32 v136, s20, v136
	v_ashrrev_i32_e32 v133, 31, v132
	v_ashrrev_i32_e32 v137, 31, v136
	v_lshlrev_b64 v[132:133], 6, v[132:133]
	v_lshlrev_b64 v[136:137], 6, v[136:137]
	v_lshl_add_u64 v[132:133], v[146:147], 0, v[132:133]
	v_lshl_add_u64 v[136:137], v[146:147], 0, v[136:137]
	global_load_dwordx4 v[132:135], v[132:133], off
	v_add_u32_e32 v227, 32, v198
	global_load_dwordx4 v[136:139], v[136:137], off
	v_add_u32_e32 v226, 48, v198
	v_cmp_gt_u32_e64 s[54:55], s97, v227
	v_add_u32_e32 v225, 64, v198
	v_cmp_gt_u32_e64 s[50:51], s97, v226
	v_cndmask_b32_e64 v152, 0, v227, s[54:55]
	v_cmp_gt_u32_e64 s[48:49], s97, v225
	v_cndmask_b32_e64 v153, 0, v226, s[50:51]
	v_add_u32_e32 v152, s20, v152
	v_cndmask_b32_e64 v155, 0, v225, s[48:49]
	v_add_u32_e32 v154, s20, v153
	v_ashrrev_i32_e32 v153, 31, v152
	v_add_u32_e32 v156, s20, v155
	v_ashrrev_i32_e32 v155, 31, v154
	v_lshlrev_b64 v[152:153], 6, v[152:153]
	v_lshlrev_b64 v[154:155], 6, v[154:155]
	v_add_u32_e32 v224, 0x50, v198
	v_cmp_gt_u32_e64 s[46:47], s97, v224
	s_mov_b32 s44, 0x358637bd
	v_add_u32_e32 v222, 0x60, v198
	v_add_u32_e32 v199, 0x70, v198
	v_cndmask_b32_e64 v157, 0, v224, s[46:47]
	v_mov_b64_e32 v[188:189], s[44:45]
	v_cmp_gt_u32_e64 s[44:45], s97, v222
	v_cmp_gt_u32_e32 vcc, s97, v199
	v_add_u32_e32 v158, s20, v157
	v_ashrrev_i32_e32 v157, 31, v156
	v_cndmask_b32_e64 v159, 0, v222, s[44:45]
	v_cndmask_b32_e32 v161, 0, v199, vcc
	v_lshlrev_b64 v[156:157], 6, v[156:157]
	s_mov_b32 s90, 0x3a800000
	v_add_u32_e32 v160, s20, v159
	v_add_u32_e32 v162, s20, v161
	v_ashrrev_i32_e32 v159, 31, v158
	v_ashrrev_i32_e32 v161, 31, v160
	v_ashrrev_i32_e32 v163, 31, v162
	v_lshlrev_b64 v[158:159], 6, v[158:159]
	v_lshlrev_b64 v[160:161], 6, v[160:161]
	v_lshlrev_b64 v[162:163], 6, v[162:163]
	v_lshl_add_u64 v[252:253], v[146:147], 0, v[152:153]
	global_load_dwordx4 v[176:179], v[252:253], off
	v_lshl_add_u64 v[252:253], v[146:147], 0, v[154:155]
	global_load_dwordx4 v[180:183], v[252:253], off
	v_lshl_add_u64 v[252:253], v[146:147], 0, v[156:157]
	global_load_dwordx4 v[184:187], v[252:253], off
	v_lshl_add_u64 v[252:253], v[146:147], 0, v[158:159]
	global_load_dwordx4 v[240:243], v[252:253], off
	v_lshl_add_u64 v[252:253], v[146:147], 0, v[160:161]
	global_load_dwordx4 v[244:247], v[252:253], off
	v_lshl_add_u64 v[252:253], v[146:147], 0, v[162:163]
	global_load_dwordx4 v[248:251], v[252:253], off
	s_waitcnt vmcnt(0) lgkmcnt(0)
	v_add_f32_e32 v174, v133, v132
	v_add_f32_e32 v175, v134, v135
	v_add_f32_e32 v133, v174, v175
	v_add_f32_e32 v174, v137, v136
	v_add_f32_e32 v175, v138, v139
	v_add_f32_e32 v132, v174, v175
	v_lshl_add_u64 v[136:137], v[146:147], 0, v[152:153]
	v_lshl_add_u64 v[138:139], v[146:147], 0, v[154:155]
	v_mov_b64_e32 v[190:191], v[176:177]
	v_mov_b64_e32 v[192:193], v[178:179]
	v_mov_b64_e32 v[228:229], v[180:181]
	v_mov_b64_e32 v[230:231], v[182:183]
	ds_bpermute_b32 v135, v195, v133
	ds_bpermute_b32 v134, v195, v132
	v_lshl_add_u64 v[136:137], v[146:147], 0, v[156:157]
	v_lshl_add_u64 v[138:139], v[146:147], 0, v[158:159]
	v_lshl_add_u64 v[152:153], v[146:147], 0, v[160:161]
	v_lshl_add_u64 v[154:155], v[146:147], 0, v[162:163]
	s_waitcnt lgkmcnt(0)
	v_pk_add_f32 v[132:133], v[132:133], v[134:135]
	ds_bpermute_b32 v135, v196, v133
	ds_bpermute_b32 v134, v196, v132
	s_waitcnt lgkmcnt(0)
	v_pk_add_f32 v[132:133], v[132:133], v[134:135]
	s_nop 0
	v_pk_fma_f32 v[156:157], v[132:133], s[90:91], v[188:189] op_sel_hi:[1,0,0]
	s_nop 0
	v_mul_f32_e32 v132, 0x4b800000, v157
	v_cmp_gt_f32_e64 s[58:59], s29, v157
	s_nop 1
	v_cndmask_b32_e64 v132, v157, v132, s[58:59]
	v_rsq_f32_e32 v157, v132
	v_mov_b64_e32 v[232:233], v[184:185]
	v_mov_b64_e32 v[234:235], v[186:187]
	v_mov_b64_e32 v[236:237], v[240:241]
	v_mov_b64_e32 v[238:239], v[242:243]
	s_nop 0
	v_mov_b64_e32 v[136:137], v[244:245]
	v_mov_b64_e32 v[138:139], v[246:247]
	v_mov_b64_e32 v[132:133], v[248:249]
	v_mov_b64_e32 v[134:135], v[250:251]
	v_mul_f32_e32 v152, 0x45800000, v157
	v_cndmask_b32_e64 v153, v157, v152, s[58:59]
	v_mul_f32_e32 v157, v122, v153
	v_cndmask_b32_e64 v153, 0, v153, s[56:57]
	v_mul_legacy_f32 v122, v126, v153
	v_mul_legacy_f32 v152, v108, v153
	v_mul_f32_e32 v108, v109, v153
	v_mul_f32_e32 v109, 0x4b800000, v156
	v_cmp_gt_f32_e64 s[58:59], s29, v156
	v_cndmask_b32_e64 v109, v156, v109, s[58:59]
	v_rsq_f32_e32 v109, v109
	v_mul_legacy_f32 v182, v128, v153
	v_cndmask_b32_e64 v128, 0, v108, s[56:57]
	v_mul_legacy_f32 v160, v130, v153
	v_mul_legacy_f32 v130, v124, v153
	v_mul_legacy_f32 v124, v110, v153
	v_mul_legacy_f32 v110, v111, v153
	v_mul_f32_e32 v108, 0x45800000, v109
	v_cndmask_b32_e64 v108, v109, v108, s[58:59]
	v_cndmask_b32_e64 v108, 0, v108, s[52:53]
	v_mul_legacy_f32 v187, v116, v108
	v_mul_legacy_f32 v181, v117, v108
	v_mul_legacy_f32 v175, v118, v108
	v_cndmask_b32_e64 v162, 0, v157, s[56:57]
	v_mul_legacy_f32 v157, v119, v108
	v_mul_legacy_f32 v119, v112, v108
	v_mul_legacy_f32 v117, v113, v108
	v_mul_legacy_f32 v186, v104, v108
	v_mul_legacy_f32 v113, v114, v108
	v_mul_f32_e32 v109, v115, v108
	v_mul_legacy_f32 v180, v105, v108
	v_mul_legacy_f32 v174, v106, v108
	v_mul_legacy_f32 v156, v107, v108
	v_mul_legacy_f32 v118, v92, v108
	s_waitcnt vmcnt(0)
; __device__ __forceinline__ float bperm_f(int src_lane, float v) { return __builtin_bit_cast(float, __builtin_amdgcn_ds_bpermute(src_lane << 2, __builtin_bit_cast(int, v))); }
;     __device__ __forceinline__ void operator()(Acc& acc, const Unit& u, int wr, int wc, int fr, int fq) const {
;     ...
;           for (int q = 0; q < 8; ++q) {
;             const int t = tbase + 16 * q; const bool ok = (t >= 0) && (t < SEQ);
;             float sq = (pq[q][0] + pq[q][1]) + (pq[q][2] + pq[q][3]); sq += bperm_f(ln ^ 16, sq); sq += bperm_f(ln ^ 32, sq);
;             const float rs = rsqrtf(sq * (1.0f / DM) + EPS);
; #pragma unroll
;             for (int bj = 0; bj < 2; ++bj)
; #pragma unroll
;                 for (int n = 0; n < 2; ++n)
; #pragma unroll
;                     for (int i = 0; i < 4; ++i) { const float v = acc[q >> 2][bj][q & 3][n][i]; acc[q >> 2][bj][q & 3][n][i] = ok ? v * rs : 0.f; }
	v_add_f32_e32 v114, v191, v190
	v_add_f32_e32 v115, v192, v193
	v_add_f32_e32 v105, v114, v115
	v_add_f32_e32 v114, v229, v228
	v_add_f32_e32 v115, v230, v231
	v_add_f32_e32 v104, v114, v115
	ds_bpermute_b32 v115, v195, v105
	ds_bpermute_b32 v114, v195, v104
	v_mul_legacy_f32 v116, v93, v108
	s_waitcnt lgkmcnt(0)
	v_pk_add_f32 v[104:105], v[104:105], v[114:115]
	ds_bpermute_b32 v107, v196, v105
	ds_bpermute_b32 v106, v196, v104
	v_mul_f32_e32 v155, v120, v153
	v_mul_legacy_f32 v178, v121, v153
	s_waitcnt lgkmcnt(0)
	v_pk_add_f32 v[92:93], v[104:105], v[106:107]
	v_mul_legacy_f32 v176, v129, v153
	v_pk_fma_f32 v[92:93], v[92:93], s[90:91], v[188:189] op_sel_hi:[1,0,0]
	v_mul_legacy_f32 v154, v131, v153
	v_mul_legacy_f32 v126, v125, v153
	v_mul_legacy_f32 v120, v127, v153
	v_cndmask_b32_e64 v184, 0, v155, s[56:57]
	v_mul_legacy_f32 v158, v123, v153
	v_mul_f32_e32 v104, 0x4b800000, v93
	v_cmp_gt_f32_e64 s[56:57], s29, v93
	v_mul_legacy_f32 v112, v94, v108
	v_cndmask_b32_e64 v93, v93, v104, s[56:57]
	v_rsq_f32_e32 v93, v93
	v_mul_legacy_f32 v108, v95, v108
	v_cndmask_b32_e64 v109, 0, v109, s[52:53]
	v_mul_f32_e32 v94, 0x45800000, v93
	v_cndmask_b32_e64 v111, v93, v94, s[56:57]
	v_mul_f32_e32 v93, v100, v111
	v_cndmask_b32_e64 v111, 0, v111, s[54:55]
	v_mul_legacy_f32 v100, v76, v111
	v_mul_f32_e32 v76, v77, v111
	v_mul_f32_e32 v77, 0x4b800000, v92
	v_cmp_gt_f32_e64 s[52:53], s29, v92
	v_cndmask_b32_e64 v115, 0, v93, s[54:55]
	v_cndmask_b32_e64 v77, v92, v77, s[52:53]
	v_mul_legacy_f32 v107, v101, v111
	v_rsq_f32_e32 v77, v77
	v_mul_legacy_f32 v105, v102, v111
	v_mul_legacy_f32 v103, v103, v111
	v_mul_f32_e32 v93, v96, v111
	v_cndmask_b32_e64 v96, 0, v76, s[54:55]
	v_mul_legacy_f32 v94, v78, v111
	v_mul_legacy_f32 v92, v79, v111
	v_mul_f32_e32 v76, 0x45800000, v77
	v_cndmask_b32_e64 v101, 0, v93, s[54:55]
	v_cndmask_b32_e64 v76, v77, v76, s[52:53]
	v_mul_legacy_f32 v97, v97, v111
	v_mul_legacy_f32 v114, v88, v111
	v_mul_legacy_f32 v95, v98, v111
	v_mul_f32_e32 v93, v99, v111
	v_mul_legacy_f32 v106, v89, v111
	v_cndmask_b32_e64 v76, 0, v76, s[50:51]
	v_mul_legacy_f32 v99, v84, v76
	v_mul_legacy_f32 v104, v90, v111
	v_mul_f32_e32 v88, v91, v111
	v_mul_legacy_f32 v91, v85, v76
	v_mul_legacy_f32 v89, v86, v76
	v_mul_legacy_f32 v87, v87, v76
	v_mul_legacy_f32 v85, v80, v76
	v_mul_legacy_f32 v81, v81, v76
	v_mul_legacy_f32 v98, v72, v76
	v_mul_legacy_f32 v79, v82, v76
	v_mul_f32_e32 v77, v83, v76
	v_mul_legacy_f32 v90, v73, v76
	v_add_f32_e32 v82, v233, v232
	v_add_f32_e32 v83, v234, v235
	v_add_f32_e32 v73, v82, v83
	v_add_f32_e32 v82, v237, v236
	v_add_f32_e32 v83, v238, v239
	v_add_f32_e32 v72, v82, v83
	ds_bpermute_b32 v83, v195, v73
	ds_bpermute_b32 v82, v195, v72
	v_cndmask_b32_e64 v102, 0, v88, s[54:55]
	v_mul_legacy_f32 v88, v74, v76
	s_waitcnt lgkmcnt(0)
	v_pk_add_f32 v[72:73], v[72:73], v[82:83]
	v_mul_legacy_f32 v86, v75, v76
	ds_bpermute_b32 v75, v196, v73
	ds_bpermute_b32 v74, v196, v72
	v_mul_legacy_f32 v84, v68, v76
	v_mul_legacy_f32 v80, v69, v76
	s_waitcnt lgkmcnt(0)
	v_pk_add_f32 v[68:69], v[72:73], v[74:75]
	v_mul_f32_e32 v70, v70, v76
	v_pk_fma_f32 v[82:83], v[68:69], s[90:91], v[188:189] op_sel_hi:[1,0,0]
	v_mul_f32_e32 v68, 0x4b800000, v83
	v_cmp_gt_f32_e64 s[52:53], s29, v83
	v_mul_legacy_f32 v76, v71, v76
	v_cndmask_b32_e64 v77, 0, v77, s[50:51]
	v_cndmask_b32_e64 v68, v83, v68, s[52:53]
	v_rsq_f32_e32 v68, v68
	v_cndmask_b32_e64 v78, 0, v70, s[50:51]
	v_cmp_gt_f32_e64 s[50:51], s29, v82
	v_cndmask_b32_e64 v93, 0, v93, s[54:55]
	v_mul_f32_e32 v69, 0x45800000, v68
	v_cndmask_b32_e64 v83, v68, v69, s[52:53]
	v_cndmask_b32_e64 v83, 0, v83, s[48:49]
	v_mul_legacy_f32 v68, v44, v83
	v_mul_f32_e32 v44, v45, v83
	v_mul_f32_e32 v45, 0x4b800000, v82
	v_cndmask_b32_e64 v45, v82, v45, s[50:51]
	v_mul_legacy_f32 v191, v64, v83
	v_rsq_f32_e32 v45, v45
	v_mul_legacy_f32 v75, v65, v83
	v_mul_legacy_f32 v69, v60, v83
	v_mul_legacy_f32 v73, v66, v83
	v_mul_f32_e32 v64, v67, v83
	v_mul_legacy_f32 v67, v61, v83
	v_cndmask_b32_e64 v66, 0, v44, s[48:49]
	v_cndmask_b32_e64 v71, 0, v64, s[48:49]
	v_mul_legacy_f32 v65, v62, v83
	v_mul_legacy_f32 v64, v46, v83
	v_mul_legacy_f32 v61, v63, v83
	v_mul_legacy_f32 v60, v47, v83
	v_mul_f32_e32 v44, 0x45800000, v45
	v_cndmask_b32_e64 v44, v45, v44, s[50:51]
	v_mul_legacy_f32 v190, v56, v83
	v_mul_legacy_f32 v74, v57, v83
	v_cndmask_b32_e64 v44, 0, v44, s[46:47]
	v_mul_legacy_f32 v193, v52, v44
	v_mul_legacy_f32 v72, v58, v83
	v_mul_f32_e32 v56, v59, v83
	v_mul_legacy_f32 v59, v53, v44
	v_mul_legacy_f32 v57, v54, v44
	v_mul_legacy_f32 v55, v55, v44
	v_mul_legacy_f32 v53, v48, v44
	v_mul_legacy_f32 v49, v49, v44
	v_mul_legacy_f32 v192, v40, v44
	v_mul_legacy_f32 v47, v50, v44
	v_mul_f32_e32 v45, v51, v44
	v_mul_legacy_f32 v58, v41, v44
	v_add_f32_e32 v50, v137, v136
	v_add_f32_e32 v51, v138, v139
	v_add_f32_e32 v41, v50, v51
	v_add_f32_e32 v50, v133, v132
	v_add_f32_e32 v51, v134, v135
	v_add_f32_e32 v40, v50, v51
	ds_bpermute_b32 v51, v195, v41
	ds_bpermute_b32 v50, v195, v40
	v_cndmask_b32_e64 v70, 0, v56, s[48:49]
	v_mul_legacy_f32 v56, v42, v44
	s_waitcnt lgkmcnt(0)
	v_pk_add_f32 v[40:41], v[40:41], v[50:51]
	v_mul_legacy_f32 v54, v43, v44
	ds_bpermute_b32 v43, v196, v41
	ds_bpermute_b32 v42, v196, v40
	v_mul_legacy_f32 v52, v28, v44
	v_mul_legacy_f32 v48, v29, v44
	s_waitcnt lgkmcnt(0)
; __device__ __forceinline__ float sigmoidf_(float x) { return __builtin_amdgcn_rcpf(1.0f + __expf(-x)); }
; template <int N> __device__ __forceinline__ float dpp_ror(float v) { return __builtin_bit_cast(float, __builtin_amdgcn_update_dpp(0, __builtin_bit_cast(int, v), 0x120 + N, 0xf, 0xf, false)); }
;     __device__ __forceinline__ void operator()(Acc& acc, const Unit& u, int wr, int wc, int fr, int fq) const {
;     ...
;           for (int q = 0; q < 8; ++q) {
;             const int t = tbase + 16 * q; const bool ok = (t >= 0) && (t < SEQ);
;             float sq = (pq[q][0] + pq[q][1]) + (pq[q][2] + pq[q][3]); sq += bperm_f(ln ^ 16, sq); sq += bperm_f(ln ^ 32, sq);
;             const float rs = rsqrtf(sq * (1.0f / DM) + EPS);
; #pragma unroll
;             for (int bj = 0; bj < 2; ++bj)
; #pragma unroll
;                 for (int n = 0; n < 2; ++n)
; #pragma unroll
;                     for (int i = 0; i < 4; ++i) { const float v = acc[q >> 2][bj][q & 3][n][i]; acc[q >> 2][bj][q & 3][n][i] = ok ? v * rs : 0.f; }
;     ...
;             for (int i = 0; i < 4; ++i) {
;                 const int cg_ = ch0 + 4 * n + i, cv_ = DFF + cg_;
;                 const float g0 = cw[cg_], g1 = cw[NUP + cg_], g2 = cw[2 * NUP + cg_], gb = cb[cg_];
;                 const float v0 = cw[cv_], v1 = cw[NUP + cv_], v2 = cw[2 * NUP + cv_], vb = cb[cv_];
;                 float pg1 = 0.f, pg2 = 0.f, pv1 = 0.f, pv2 = 0.f;
; #pragma unroll
;                 for (int q = 0; q < 8; ++q) {
;                     float cgv = acc[q >> 2][0][q & 3][n][i], cvv = acc[q >> 2][1][q & 3][n][i];
;                     asm volatile("" : "+v"(cgv), "+v"(cvv) : "v"(chain));
;                     const float tg1 = dpp_ror<1>(cgv), tg2 = dpp_ror<2>(cgv), tv1 = dpp_ror<1>(cvv), tv2 = dpp_ror<2>(cvv);
;                     const float sg1 = fr >= 1 ? tg1 : pg1, sg2 = fr >= 2 ? tg2 : pg2, sv1 = fr >= 1 ? tv1 : pv1, sv2 = fr >= 2 ? tv2 : pv2;
;                     const float gg = gb + g0 * sg2 + g1 * sg1 + g2 * cgv;
;                     const float vv = vb + v0 * sv2 + v1 * sv1 + v2 * cvv;
;                     chain = gg * sigmoidf_(gg) * vv; acc[q >> 2][0][q & 3][n][i] = chain;
;                     pg1 = tg1; pg2 = tg2; pv1 = tv1; pv2 = tv2;
;                 }
	v_pk_add_f32 v[28:29], v[40:41], v[42:43]
	v_pk_fma_f32 v[28:29], v[28:29], s[90:91], v[188:189] op_sel_hi:[1,0,0]
	v_mul_legacy_f32 v46, v30, v44
	v_mul_f32_e32 v40, 0x4b800000, v29
	v_cmp_gt_f32_e64 s[48:49], s29, v29
	v_mul_legacy_f32 v44, v31, v44
	v_cndmask_b32_e64 v29, v29, v40, s[48:49]
	v_rsq_f32_e32 v29, v29
	v_cndmask_b32_e64 v45, 0, v45, s[46:47]
	v_cmp_gt_f32_e64 s[46:47], s29, v28
	v_mul_f32_e32 v30, 0x45800000, v29
	v_cndmask_b32_e64 v40, v29, v30, s[48:49]
	v_mul_f32_e32 v29, v36, v40
	v_cndmask_b32_e64 v40, 0, v40, s[44:45]
	v_mul_legacy_f32 v36, v12, v40
	v_mul_f32_e32 v12, v13, v40
	v_mul_f32_e32 v13, 0x4b800000, v28
	v_cndmask_b32_e64 v133, 0, v29, s[44:45]
	v_cndmask_b32_e64 v13, v28, v13, s[46:47]
	v_mul_legacy_f32 v63, v37, v40
	v_rsq_f32_e32 v13, v13
	v_mul_legacy_f32 v43, v38, v40
	v_mul_legacy_f32 v39, v39, v40
	v_mul_f32_e32 v29, v32, v40
	v_cndmask_b32_e64 v32, 0, v12, s[44:45]
	v_mul_legacy_f32 v30, v14, v40
	v_mul_legacy_f32 v28, v15, v40
	v_mul_f32_e32 v12, 0x45800000, v13
	v_cndmask_b32_e64 v12, v13, v12, s[46:47]
	v_cndmask_b32_e32 v12, 0, v12, vcc
	v_mul_legacy_f32 v135, v20, v12
	v_mul_legacy_f32 v83, v21, v12
	v_cndmask_b32_e64 v37, 0, v29, s[44:45]
	v_mul_legacy_f32 v51, v22, v12
	v_mul_legacy_f32 v33, v33, v40
	v_mul_legacy_f32 v132, v24, v40
	v_mul_legacy_f32 v41, v23, v12
	v_mul_legacy_f32 v31, v34, v40
	v_mul_f32_e32 v29, v35, v40
	v_mul_legacy_f32 v62, v25, v40
	v_mul_legacy_f32 v35, v16, v12
	v_mul_legacy_f32 v134, v8, v12
	v_mul_legacy_f32 v34, v4, v12
	v_mul_legacy_f32 v42, v26, v40
	v_mul_f32_e32 v24, v27, v40
	v_mul_legacy_f32 v27, v17, v12
	v_mul_legacy_f32 v82, v9, v12
	v_mul_legacy_f32 v26, v5, v12
	v_mul_legacy_f32 v15, v18, v12
	v_mul_legacy_f32 v50, v10, v12
	v_mul_legacy_f32 v14, v6, v12
	v_cndmask_b32_e64 v29, 0, v29, s[44:45]
	v_cndmask_b32_e64 v38, 0, v24, s[44:45]
	v_mul_legacy_f32 v13, v19, v12
	v_mul_legacy_f32 v40, v11, v12
	v_mul_legacy_f32 v12, v7, v12
	v_lshl_or_b32 v4, s34, 7, v2
	v_ashrrev_i32_e32 v5, 31, v4
	v_lshlrev_b64 v[16:17], 2, v[4:5]
	v_lshl_add_u64 v[6:7], s[36:37], 0, v[16:17]
	s_movk_i32 s21, 0x5000
	v_add_co_u32_e32 v8, vcc, s21, v6
	s_mov_b32 s21, 0xb000
	s_nop 0
	v_addc_co_u32_e32 v9, vcc, 0, v7, vcc
	v_add_co_u32_e32 v10, vcc, s21, v6
	v_lshl_add_u64 v[16:17], s[60:61], 0, v[16:17]
	s_nop 0
	v_addc_co_u32_e32 v11, vcc, 0, v7, vcc
	global_load_dword v139, v[6:7], off
	global_load_dword v137, v[8:9], off offset:2048
	global_load_dword v136, v[10:11], off
	global_load_dword v189, v[16:17], off
	v_add_co_u32_e32 v18, vcc, s97, v6
	s_mov_b32 s21, 0xd000
	s_nop 0
	v_addc_co_u32_e32 v19, vcc, 0, v7, vcc
	v_add_co_u32_e32 v22, vcc, s80, v6
	global_load_dword v138, v[18:19], off offset:3072
	s_nop 0
	v_addc_co_u32_e32 v23, vcc, 0, v7, vcc
	v_add_co_u32_e32 v20, vcc, s97, v16
	s_nop 0
	s_nop 0
	v_addc_co_u32_e32 v21, vcc, 0, v17, vcc
	v_add_co_u32_e32 v24, vcc, s21, v6
	global_load_dword v188, v[20:21], off offset:3072
	s_nop 0
	v_addc_co_u32_e32 v25, vcc, 0, v7, vcc
	global_load_dword v229, v[22:23], off offset:1024
	global_load_dword v228, v[24:25], off offset:3072
	global_load_dword v232, v[6:7], off offset:4
	global_load_dword v233, v[8:9], off offset:2052
	global_load_dword v234, v[10:11], off offset:4
	global_load_dword v235, v[16:17], off offset:4
	global_load_dword v236, v[20:21], off offset:3076
	global_load_dword v237, v[18:19], off offset:3076
	global_load_dword v238, v[22:23], off offset:1028
	global_load_dword v239, v[24:25], off offset:3076
	s_nop 0
	v_mov_b32_dpp v111, v182 row_ror:1 row_mask:0xf bank_mask:0xf
	v_mov_b32_dpp v121, v182 row_ror:2 row_mask:0xf bank_mask:0xf
	v_cndmask_b32_e64 v183, v111, 0, s[38:39]
	v_cndmask_b32_e64 v155, 0, v121, s[40:41]
	v_mov_b32_dpp v123, v184 row_ror:1 row_mask:0xf bank_mask:0xf
	v_mov_b32_dpp v125, v184 row_ror:2 row_mask:0xf bank_mask:0xf
	v_cndmask_b32_e64 v185, v123, 0, s[38:39]
	v_cndmask_b32_e64 v159, 0, v125, s[40:41]
	s_waitcnt vmcnt(13)
	v_pk_mul_f32 v[182:183], v[136:137], v[182:183]
	s_waitcnt vmcnt(12)
	v_fma_f32 v155, v139, v155, v189
	v_add_f32_e32 v155, v183, v155
	v_add_f32_e32 v155, v182, v155
	v_mul_f32_e32 v161, 0xbfb8aa3b, v155
	v_exp_f32_e32 v161, v161
	v_mov_b32_e32 v183, v136
	v_add_f32_e32 v136, 1.0, v161
	v_rcp_f32_e32 v161, v136
	s_waitcnt vmcnt(10)
	v_fma_f32 v159, v138, v159, v188
	v_mul_f32_e32 v155, v155, v161
	s_waitcnt vmcnt(9)
	v_mov_b32_e32 v136, v229
	s_waitcnt vmcnt(8)
; __device__ __forceinline__ float sigmoidf_(float x) { return __builtin_amdgcn_rcpf(1.0f + __expf(-x)); }
; template <int N> __device__ __forceinline__ float dpp_ror(float v) { return __builtin_bit_cast(float, __builtin_amdgcn_update_dpp(0, __builtin_bit_cast(int, v), 0x120 + N, 0xf, 0xf, false)); }
;     __device__ __forceinline__ void operator()(Acc& acc, const Unit& u, int wr, int wc, int fr, int fq) const {
;     ...
;         for (int n = 0; n < 2; ++n) {
; #pragma unroll
;             for (int i = 0; i < 4; ++i) {
;                 const int cg_ = ch0 + 4 * n + i, cv_ = DFF + cg_;
;                 const float g0 = cw[cg_], g1 = cw[NUP + cg_], g2 = cw[2 * NUP + cg_], gb = cb[cg_];
;                 const float v0 = cw[cv_], v1 = cw[NUP + cv_], v2 = cw[2 * NUP + cv_], vb = cb[cv_];
;                 float pg1 = 0.f, pg2 = 0.f, pv1 = 0.f, pv2 = 0.f;
; #pragma unroll
;                 for (int q = 0; q < 8; ++q) {
;                     float cgv = acc[q >> 2][0][q & 3][n][i], cvv = acc[q >> 2][1][q & 3][n][i];
;                     asm volatile("" : "+v"(cgv), "+v"(cvv) : "v"(chain));
;                     const float tg1 = dpp_ror<1>(cgv), tg2 = dpp_ror<2>(cgv), tv1 = dpp_ror<1>(cvv), tv2 = dpp_ror<2>(cvv);
;                     const float sg1 = fr >= 1 ? tg1 : pg1, sg2 = fr >= 2 ? tg2 : pg2, sv1 = fr >= 1 ? tv1 : pv1, sv2 = fr >= 2 ? tv2 : pv2;
;                     const float gg = gb + g0 * sg2 + g1 * sg1 + g2 * cgv;
;                     const float vv = vb + v0 * sv2 + v1 * sv1 + v2 * cvv;
;                     chain = gg * sigmoidf_(gg) * vv; acc[q >> 2][0][q & 3][n][i] = chain;
;                     pg1 = tg1; pg2 = tg2; pv1 = tv1; pv2 = tv2;
;                 }
;                 __builtin_amdgcn_sched_barrier(0);
;             }
;         }
	v_pk_mul_f32 v[184:185], v[228:229], v[184:185]
	v_mov_b32_e32 v182, v228
	v_add_f32_e32 v159, v185, v159
	v_add_f32_e32 v159, v184, v159
	v_mul_f32_e32 v184, v159, v155
	v_mov_b32_dpp v129, v187 row_ror:2 row_mask:0xf bank_mask:0xf
	v_mov_b32_dpp v153, v186 row_ror:2 row_mask:0xf bank_mask:0xf
	v_mov_b32_dpp v127, v187 row_ror:1 row_mask:0xf bank_mask:0xf
	v_mov_b32_dpp v131, v186 row_ror:1 row_mask:0xf bank_mask:0xf
	v_cndmask_b32_e64 v231, v121, v129, s[40:41]
	v_cndmask_b32_e64 v230, v125, v153, s[40:41]
	v_cndmask_b32_e64 v229, v127, v111, s[38:39]
	v_cndmask_b32_e64 v228, v131, v123, s[38:39]
	v_pk_fma_f32 v[230:231], v[138:139], v[230:231], v[188:189]
	v_pk_fma_f32 v[228:229], v[136:137], v[228:229], v[230:231]
	v_pk_fma_f32 v[186:187], v[182:183], v[186:187], v[228:229]
	v_mul_f32_e32 v111, 0xbfb8aa3b, v187
	v_exp_f32_e32 v111, v111
	s_nop 0
	v_add_f32_e32 v111, 1.0, v111
	v_rcp_f32_e32 v111, v111
	s_nop 0
	v_mul_f32_e32 v111, v187, v111
	v_mul_f32_e32 v185, v186, v111
	v_mov_b32_dpp v123, v115 row_ror:2 row_mask:0xf bank_mask:0xf
	v_mov_b32_dpp v155, v114 row_ror:2 row_mask:0xf bank_mask:0xf
	v_mov_b32_dpp v121, v115 row_ror:1 row_mask:0xf bank_mask:0xf
	v_mov_b32_dpp v125, v114 row_ror:1 row_mask:0xf bank_mask:0xf
	v_cndmask_b32_e64 v229, v129, v123, s[40:41]
	v_cndmask_b32_e64 v228, v153, v155, s[40:41]
	v_cndmask_b32_e64 v187, v121, v127, s[38:39]
	v_cndmask_b32_e64 v186, v125, v131, s[38:39]
	v_pk_fma_f32 v[228:229], v[138:139], v[228:229], v[188:189]
	v_pk_fma_f32 v[186:187], v[136:137], v[186:187], v[228:229]
	v_pk_fma_f32 v[114:115], v[182:183], v[114:115], v[186:187]
	v_mul_f32_e32 v111, 0xbfb8aa3b, v115
	v_exp_f32_e32 v111, v111
	s_nop 0
	v_add_f32_e32 v111, 1.0, v111
	v_rcp_f32_e32 v111, v111
	s_nop 0
	v_mul_f32_e32 v111, v115, v111
	v_mul_f32_e32 v186, v114, v111
	v_mov_b32_dpp v129, v99 row_ror:2 row_mask:0xf bank_mask:0xf
	v_mov_b32_dpp v153, v98 row_ror:2 row_mask:0xf bank_mask:0xf
	v_mov_b32_dpp v127, v99 row_ror:1 row_mask:0xf bank_mask:0xf
	v_mov_b32_dpp v131, v98 row_ror:1 row_mask:0xf bank_mask:0xf
	v_cndmask_b32_e64 v229, v123, v129, s[40:41]
	v_cndmask_b32_e64 v228, v155, v153, s[40:41]
	v_cndmask_b32_e64 v115, v127, v121, s[38:39]
	v_cndmask_b32_e64 v114, v131, v125, s[38:39]
	v_pk_fma_f32 v[228:229], v[138:139], v[228:229], v[188:189]
	v_pk_fma_f32 v[114:115], v[136:137], v[114:115], v[228:229]
	v_pk_fma_f32 v[98:99], v[182:183], v[98:99], v[114:115]
	v_mul_f32_e32 v111, 0xbfb8aa3b, v99
	v_exp_f32_e32 v111, v111
	s_nop 0
	v_add_f32_e32 v111, 1.0, v111
	v_rcp_f32_e32 v111, v111
	s_nop 0
	v_mul_f32_e32 v99, v99, v111
	v_mul_f32_e32 v187, v98, v99
	v_mov_b32_dpp v123, v191 row_ror:2 row_mask:0xf bank_mask:0xf
	v_mov_b32_dpp v155, v190 row_ror:2 row_mask:0xf bank_mask:0xf
	v_mov_b32_dpp v121, v191 row_ror:1 row_mask:0xf bank_mask:0xf
	v_mov_b32_dpp v125, v190 row_ror:1 row_mask:0xf bank_mask:0xf
	v_cndmask_b32_e64 v115, v129, v123, s[40:41]
	v_cndmask_b32_e64 v114, v153, v155, s[40:41]
	v_cndmask_b32_e64 v99, v121, v127, s[38:39]
	v_cndmask_b32_e64 v98, v125, v131, s[38:39]
	v_pk_fma_f32 v[114:115], v[138:139], v[114:115], v[188:189]
	v_pk_fma_f32 v[98:99], v[136:137], v[98:99], v[114:115]
	v_pk_fma_f32 v[98:99], v[182:183], v[190:191], v[98:99]
	v_mul_f32_e32 v111, 0xbfb8aa3b, v99
	v_exp_f32_e32 v111, v111
	s_nop 0
	v_add_f32_e32 v111, 1.0, v111
	v_rcp_f32_e32 v111, v111
	s_nop 0
	v_mul_f32_e32 v99, v99, v111
	v_mul_f32_e32 v190, v98, v99
	v_mov_b32_dpp v129, v193 row_ror:2 row_mask:0xf bank_mask:0xf
	v_mov_b32_dpp v153, v192 row_ror:2 row_mask:0xf bank_mask:0xf
	v_mov_b32_dpp v127, v193 row_ror:1 row_mask:0xf bank_mask:0xf
	v_mov_b32_dpp v131, v192 row_ror:1 row_mask:0xf bank_mask:0xf
	v_cndmask_b32_e64 v115, v123, v129, s[40:41]
	v_cndmask_b32_e64 v114, v155, v153, s[40:41]
	v_cndmask_b32_e64 v99, v127, v121, s[38:39]
	v_cndmask_b32_e64 v98, v131, v125, s[38:39]
	v_pk_fma_f32 v[114:115], v[138:139], v[114:115], v[188:189]
	v_pk_fma_f32 v[98:99], v[136:137], v[98:99], v[114:115]
	v_pk_fma_f32 v[98:99], v[182:183], v[192:193], v[98:99]
	v_mul_f32_e32 v111, 0xbfb8aa3b, v99
	v_exp_f32_e32 v111, v111
	s_nop 0
	v_add_f32_e32 v111, 1.0, v111
	v_rcp_f32_e32 v111, v111
	s_nop 0
	v_mul_f32_e32 v99, v99, v111
	v_mul_f32_e32 v191, v98, v99
	v_mov_b32_dpp v123, v133 row_ror:2 row_mask:0xf bank_mask:0xf
	v_mov_b32_dpp v155, v132 row_ror:2 row_mask:0xf bank_mask:0xf
	v_mov_b32_dpp v121, v133 row_ror:1 row_mask:0xf bank_mask:0xf
	v_mov_b32_dpp v125, v132 row_ror:1 row_mask:0xf bank_mask:0xf
	v_cndmask_b32_e64 v115, v129, v123, s[40:41]
	v_cndmask_b32_e64 v114, v153, v155, s[40:41]
	v_cndmask_b32_e64 v99, v121, v127, s[38:39]
	v_cndmask_b32_e64 v98, v125, v131, s[38:39]
	v_pk_fma_f32 v[114:115], v[138:139], v[114:115], v[188:189]
	v_pk_fma_f32 v[98:99], v[136:137], v[98:99], v[114:115]
	v_pk_fma_f32 v[98:99], v[182:183], v[132:133], v[98:99]
	v_mul_f32_e32 v111, 0xbfb8aa3b, v99
	v_exp_f32_e32 v111, v111
	s_nop 0
	v_add_f32_e32 v111, 1.0, v111
	v_rcp_f32_e32 v111, v111
	s_nop 0
	v_mul_f32_e32 v99, v99, v111
	v_mul_f32_e32 v192, v98, v99
	v_mov_b32_dpp v114, v135 row_ror:1 row_mask:0xf bank_mask:0xf
	v_mov_b32_dpp v115, v135 row_ror:2 row_mask:0xf bank_mask:0xf
	v_mov_b32_dpp v129, v134 row_ror:2 row_mask:0xf bank_mask:0xf
	v_mov_b32_dpp v127, v134 row_ror:1 row_mask:0xf bank_mask:0xf
	v_cndmask_b32_e64 v99, v114, v121, s[38:39]
	v_cndmask_b32_e64 v115, v123, v115, s[40:41]
	v_cndmask_b32_e64 v114, v155, v129, s[40:41]
	v_cndmask_b32_e64 v98, v127, v125, s[38:39]
	v_pk_fma_f32 v[114:115], v[138:139], v[114:115], v[188:189]
	s_nop 0
	v_pk_fma_f32 v[98:99], v[136:137], v[98:99], v[114:115]
	s_nop 0
	v_pk_fma_f32 v[98:99], v[182:183], v[134:135], v[98:99]
	s_nop 0
	v_mul_f32_e32 v111, 0xbfb8aa3b, v99
	v_exp_f32_e32 v111, v111
	s_nop 0
	v_add_f32_e32 v111, 1.0, v111
	v_rcp_f32_e32 v111, v111
	s_nop 0
	v_mul_f32_e32 v99, v99, v111
	v_mul_f32_e32 v136, v98, v99
	s_waitcnt vmcnt(0)
; __device__ __forceinline__ float sigmoidf_(float x) { return __builtin_amdgcn_rcpf(1.0f + __expf(-x)); }
; template <int N> __device__ __forceinline__ float dpp_ror(float v) { return __builtin_bit_cast(float, __builtin_amdgcn_update_dpp(0, __builtin_bit_cast(int, v), 0x120 + N, 0xf, 0xf, false)); }
;     __device__ __forceinline__ void operator()(Acc& acc, const Unit& u, int wr, int wc, int fr, int fq) const {
;     ...
;         for (int n = 0; n < 2; ++n) {
; #pragma unroll
;             for (int i = 0; i < 4; ++i) {
;                 const int cg_ = ch0 + 4 * n + i, cv_ = DFF + cg_;
;                 const float g0 = cw[cg_], g1 = cw[NUP + cg_], g2 = cw[2 * NUP + cg_], gb = cb[cg_];
;                 const float v0 = cw[cv_], v1 = cw[NUP + cv_], v2 = cw[2 * NUP + cv_], vb = cb[cv_];
;                 float pg1 = 0.f, pg2 = 0.f, pv1 = 0.f, pv2 = 0.f;
; #pragma unroll
;                 for (int q = 0; q < 8; ++q) {
;                     float cgv = acc[q >> 2][0][q & 3][n][i], cvv = acc[q >> 2][1][q & 3][n][i];
;                     asm volatile("" : "+v"(cgv), "+v"(cvv) : "v"(chain));
;                     const float tg1 = dpp_ror<1>(cgv), tg2 = dpp_ror<2>(cgv), tv1 = dpp_ror<1>(cvv), tv2 = dpp_ror<2>(cvv);
;                     const float sg1 = fr >= 1 ? tg1 : pg1, sg2 = fr >= 2 ? tg2 : pg2, sv1 = fr >= 1 ? tv1 : pv1, sv2 = fr >= 2 ? tv2 : pv2;
;                     const float gg = gb + g0 * sg2 + g1 * sg1 + g2 * cgv;
;                     const float vv = vb + v0 * sv2 + v1 * sv1 + v2 * cvv;
;                     chain = gg * sigmoidf_(gg) * vv; acc[q >> 2][0][q & 3][n][i] = chain;
;                     pg1 = tg1; pg2 = tg2; pv1 = tv1; pv2 = tv2;
;                 }
;                 __builtin_amdgcn_sched_barrier(0);
;             }
;         }
	v_mov_b32_e32 v115, v232
	v_mov_b32_e32 v99, v233
	v_mov_b32_e32 v98, v234
	v_mov_b32_e32 v133, v235
	v_mov_b32_e32 v132, v236
	v_mov_b32_e32 v114, v237
	v_mov_b32_e32 v139, v238
	v_mov_b32_e32 v138, v239
	global_load_dword v240, v[6:7], off offset:8
	global_load_dword v241, v[8:9], off offset:2056
	global_load_dword v242, v[10:11], off offset:8
	global_load_dword v243, v[16:17], off offset:8
	global_load_dword v244, v[20:21], off offset:3080
	global_load_dword v245, v[18:19], off offset:3080
	global_load_dword v246, v[22:23], off offset:1032
	global_load_dword v247, v[24:25], off offset:3080
	v_mov_b32_dpp v111, v176 row_ror:1 row_mask:0xf bank_mask:0xf
	v_mov_b32_dpp v121, v176 row_ror:2 row_mask:0xf bank_mask:0xf
	v_cndmask_b32_e64 v177, v111, 0, s[38:39]
	v_cndmask_b32_e64 v134, 0, v121, s[40:41]
	v_mov_b32_dpp v123, v178 row_ror:1 row_mask:0xf bank_mask:0xf
	v_cndmask_b32_e64 v179, v123, 0, s[38:39]
	v_mov_b32_dpp v125, v178 row_ror:2 row_mask:0xf bank_mask:0xf
	v_cndmask_b32_e64 v137, 0, v125, s[40:41]
	s_nop 0
	v_fma_f32 v155, v115, v134, v133
	v_pk_mul_f32 v[134:135], v[98:99], v[176:177]
	s_nop 0
	v_fma_f32 v137, v114, v137, v132
	v_add_f32_e32 v135, v135, v155
	v_add_f32_e32 v155, v134, v135
	v_mul_f32_e32 v134, 0xbfb8aa3b, v155
	v_exp_f32_e32 v159, v134
	v_mov_b32_e32 v135, v98
	s_nop 0
	v_pk_mul_f32 v[176:177], v[138:139], v[178:179]
	v_mov_b32_e32 v134, v138
	v_add_f32_e32 v98, 1.0, v159
	v_rcp_f32_e32 v138, v98
	v_add_f32_e32 v137, v177, v137
	v_add_f32_e32 v137, v176, v137
	v_mov_b32_e32 v98, v139
	v_mul_f32_e32 v138, v155, v138
	v_mul_f32_e32 v137, v137, v138
	v_mov_b32_dpp v129, v181 row_ror:2 row_mask:0xf bank_mask:0xf
	v_mov_b32_dpp v153, v180 row_ror:2 row_mask:0xf bank_mask:0xf
	v_mov_b32_dpp v127, v181 row_ror:1 row_mask:0xf bank_mask:0xf
	v_mov_b32_dpp v131, v180 row_ror:1 row_mask:0xf bank_mask:0xf
	v_cndmask_b32_e64 v177, v121, v129, s[40:41]
	v_cndmask_b32_e64 v176, v125, v153, s[40:41]
	v_cndmask_b32_e64 v139, v127, v111, s[38:39]
	v_cndmask_b32_e64 v138, v131, v123, s[38:39]
	v_pk_fma_f32 v[176:177], v[114:115], v[176:177], v[132:133]
	v_pk_fma_f32 v[138:139], v[98:99], v[138:139], v[176:177]
	v_pk_fma_f32 v[138:139], v[134:135], v[180:181], v[138:139]
	v_mul_f32_e32 v111, 0xbfb8aa3b, v139
	v_exp_f32_e32 v111, v111
	s_nop 0
	v_add_f32_e32 v111, 1.0, v111
	v_rcp_f32_e32 v111, v111
	s_nop 0
	v_mul_f32_e32 v111, v139, v111
	v_mul_f32_e32 v138, v138, v111
	v_mov_b32_dpp v123, v107 row_ror:2 row_mask:0xf bank_mask:0xf
	v_mov_b32_dpp v155, v106 row_ror:2 row_mask:0xf bank_mask:0xf
	v_mov_b32_dpp v121, v107 row_ror:1 row_mask:0xf bank_mask:0xf
	v_mov_b32_dpp v125, v106 row_ror:1 row_mask:0xf bank_mask:0xf
	v_cndmask_b32_e64 v179, v129, v123, s[40:41]
	v_cndmask_b32_e64 v178, v153, v155, s[40:41]
	v_cndmask_b32_e64 v177, v121, v127, s[38:39]
	v_cndmask_b32_e64 v176, v125, v131, s[38:39]
	v_pk_fma_f32 v[178:179], v[114:115], v[178:179], v[132:133]
	v_pk_fma_f32 v[176:177], v[98:99], v[176:177], v[178:179]
	v_pk_fma_f32 v[106:107], v[134:135], v[106:107], v[176:177]
	v_mul_f32_e32 v111, 0xbfb8aa3b, v107
	v_exp_f32_e32 v111, v111
	s_nop 0
	v_add_f32_e32 v111, 1.0, v111
	v_rcp_f32_e32 v111, v111
	s_nop 0
	v_mul_f32_e32 v107, v107, v111
	v_mul_f32_e32 v106, v106, v107
	v_mov_b32_dpp v129, v91 row_ror:2 row_mask:0xf bank_mask:0xf
	v_mov_b32_dpp v139, v90 row_ror:2 row_mask:0xf bank_mask:0xf
	v_mov_b32_dpp v127, v91 row_ror:1 row_mask:0xf bank_mask:0xf
	v_mov_b32_dpp v131, v90 row_ror:1 row_mask:0xf bank_mask:0xf
	v_cndmask_b32_e64 v179, v123, v129, s[40:41]
	v_cndmask_b32_e64 v178, v155, v139, s[40:41]
	v_cndmask_b32_e64 v177, v127, v121, s[38:39]
	v_cndmask_b32_e64 v176, v131, v125, s[38:39]
	v_pk_fma_f32 v[178:179], v[114:115], v[178:179], v[132:133]
	v_pk_fma_f32 v[176:177], v[98:99], v[176:177], v[178:179]
	v_pk_fma_f32 v[90:91], v[134:135], v[90:91], v[176:177]
	v_mul_f32_e32 v107, 0xbfb8aa3b, v91
	v_exp_f32_e32 v107, v107
	s_nop 0
	v_add_f32_e32 v107, 1.0, v107
	v_rcp_f32_e32 v107, v107
	s_nop 0
	v_mul_f32_e32 v91, v91, v107
	v_mul_f32_e32 v90, v90, v91
	v_mov_b32_dpp v121, v75 row_ror:2 row_mask:0xf bank_mask:0xf
	v_mov_b32_dpp v125, v74 row_ror:2 row_mask:0xf bank_mask:0xf
	v_mov_b32_dpp v111, v75 row_ror:1 row_mask:0xf bank_mask:0xf
	v_mov_b32_dpp v123, v74 row_ror:1 row_mask:0xf bank_mask:0xf
	v_cndmask_b32_e64 v179, v129, v121, s[40:41]
	v_cndmask_b32_e64 v178, v139, v125, s[40:41]
	v_cndmask_b32_e64 v177, v111, v127, s[38:39]
	v_cndmask_b32_e64 v176, v123, v131, s[38:39]
	v_pk_fma_f32 v[178:179], v[114:115], v[178:179], v[132:133]
	v_pk_fma_f32 v[176:177], v[98:99], v[176:177], v[178:179]
	v_pk_fma_f32 v[74:75], v[134:135], v[74:75], v[176:177]
	v_mul_f32_e32 v91, 0xbfb8aa3b, v75
	v_exp_f32_e32 v91, v91
	s_nop 0
	v_add_f32_e32 v91, 1.0, v91
	v_rcp_f32_e32 v91, v91
	s_nop 0
	v_mul_f32_e32 v75, v75, v91
	v_mul_f32_e32 v91, v74, v75
	v_mov_b32_dpp v129, v59 row_ror:2 row_mask:0xf bank_mask:0xf
	v_mov_b32_dpp v139, v58 row_ror:2 row_mask:0xf bank_mask:0xf
	v_mov_b32_dpp v127, v59 row_ror:1 row_mask:0xf bank_mask:0xf
	v_mov_b32_dpp v131, v58 row_ror:1 row_mask:0xf bank_mask:0xf
	v_cndmask_b32_e64 v177, v121, v129, s[40:41]
	v_cndmask_b32_e64 v176, v125, v139, s[40:41]
	v_cndmask_b32_e64 v75, v127, v111, s[38:39]
	v_cndmask_b32_e64 v74, v131, v123, s[38:39]
	v_pk_fma_f32 v[176:177], v[114:115], v[176:177], v[132:133]
	v_pk_fma_f32 v[74:75], v[98:99], v[74:75], v[176:177]
	v_pk_fma_f32 v[58:59], v[134:135], v[58:59], v[74:75]
	v_mul_f32_e32 v74, 0xbfb8aa3b, v59
	v_exp_f32_e32 v74, v74
	s_nop 0
	v_add_f32_e32 v74, 1.0, v74
	v_rcp_f32_e32 v74, v74
	s_nop 0
	v_mul_f32_e32 v59, v59, v74
	v_mul_f32_e32 v107, v58, v59
; __device__ __forceinline__ float sigmoidf_(float x) { return __builtin_amdgcn_rcpf(1.0f + __expf(-x)); }
; template <int N> __device__ __forceinline__ float dpp_ror(float v) { return __builtin_bit_cast(float, __builtin_amdgcn_update_dpp(0, __builtin_bit_cast(int, v), 0x120 + N, 0xf, 0xf, false)); }
;     __device__ __forceinline__ void operator()(Acc& acc, const Unit& u, int wr, int wc, int fr, int fq) const {
;     ...
;         for (int n = 0; n < 2; ++n) {
; #pragma unroll
;             for (int i = 0; i < 4; ++i) {
;                 const int cg_ = ch0 + 4 * n + i, cv_ = DFF + cg_;
;                 const float g0 = cw[cg_], g1 = cw[NUP + cg_], g2 = cw[2 * NUP + cg_], gb = cb[cg_];
;                 const float v0 = cw[cv_], v1 = cw[NUP + cv_], v2 = cw[2 * NUP + cv_], vb = cb[cv_];
;                 float pg1 = 0.f, pg2 = 0.f, pv1 = 0.f, pv2 = 0.f;
; #pragma unroll
;                 for (int q = 0; q < 8; ++q) {
;                     float cgv = acc[q >> 2][0][q & 3][n][i], cvv = acc[q >> 2][1][q & 3][n][i];
;                     asm volatile("" : "+v"(cgv), "+v"(cvv) : "v"(chain));
;                     const float tg1 = dpp_ror<1>(cgv), tg2 = dpp_ror<2>(cgv), tv1 = dpp_ror<1>(cvv), tv2 = dpp_ror<2>(cvv);
;                     const float sg1 = fr >= 1 ? tg1 : pg1, sg2 = fr >= 2 ? tg2 : pg2, sv1 = fr >= 1 ? tv1 : pv1, sv2 = fr >= 2 ? tv2 : pv2;
;                     const float gg = gb + g0 * sg2 + g1 * sg1 + g2 * cgv;
;                     const float vv = vb + v0 * sv2 + v1 * sv1 + v2 * cvv;
;                     chain = gg * sigmoidf_(gg) * vv; acc[q >> 2][0][q & 3][n][i] = chain;
;                     pg1 = tg1; pg2 = tg2; pv1 = tv1; pv2 = tv2;
;                 }
;                 __builtin_amdgcn_sched_barrier(0);
;             }
;         }
	v_mov_b32_dpp v121, v63 row_ror:2 row_mask:0xf bank_mask:0xf
	v_mov_b32_dpp v125, v62 row_ror:2 row_mask:0xf bank_mask:0xf
	v_mov_b32_dpp v111, v63 row_ror:1 row_mask:0xf bank_mask:0xf
	v_mov_b32_dpp v123, v62 row_ror:1 row_mask:0xf bank_mask:0xf
	v_cndmask_b32_e64 v75, v129, v121, s[40:41]
	v_cndmask_b32_e64 v74, v139, v125, s[40:41]
	v_cndmask_b32_e64 v59, v111, v127, s[38:39]
	v_cndmask_b32_e64 v58, v123, v131, s[38:39]
	v_pk_fma_f32 v[74:75], v[114:115], v[74:75], v[132:133]
	v_pk_fma_f32 v[58:59], v[98:99], v[58:59], v[74:75]
	v_pk_fma_f32 v[58:59], v[134:135], v[62:63], v[58:59]
	v_mul_f32_e32 v62, 0xbfb8aa3b, v59
	v_exp_f32_e32 v62, v62
	s_nop 0
	v_add_f32_e32 v62, 1.0, v62
	v_rcp_f32_e32 v62, v62
	s_nop 0
	v_mul_f32_e32 v59, v59, v62
	v_mul_f32_e32 v139, v58, v59
	v_mov_b32_dpp v63, v83 row_ror:1 row_mask:0xf bank_mask:0xf
	v_mov_b32_dpp v74, v83 row_ror:2 row_mask:0xf bank_mask:0xf
	v_mov_b32_dpp v127, v82 row_ror:2 row_mask:0xf bank_mask:0xf
	v_mov_b32_dpp v75, v82 row_ror:1 row_mask:0xf bank_mask:0xf
	v_cndmask_b32_e64 v59, v63, v111, s[38:39]
	v_cndmask_b32_e64 v63, v121, v74, s[40:41]
	v_cndmask_b32_e64 v62, v125, v127, s[40:41]
	v_cndmask_b32_e64 v58, v75, v123, s[38:39]
	v_pk_fma_f32 v[62:63], v[114:115], v[62:63], v[132:133]
	s_nop 0
	v_pk_fma_f32 v[58:59], v[98:99], v[58:59], v[62:63]
	s_nop 0
	v_pk_fma_f32 v[58:59], v[134:135], v[82:83], v[58:59]
	s_nop 0
	v_mul_f32_e32 v62, 0xbfb8aa3b, v59
	v_exp_f32_e32 v62, v62
	s_nop 0
	v_add_f32_e32 v62, 1.0, v62
	v_rcp_f32_e32 v62, v62
	s_nop 0
	v_mul_f32_e32 v59, v59, v62
	v_mul_f32_e32 v98, v58, v59
	s_waitcnt vmcnt(0)
	v_mov_b32_e32 v63, v240
	v_mov_b32_e32 v59, v241
	v_mov_b32_e32 v58, v242
	v_mov_b32_e32 v75, v243
	v_mov_b32_e32 v74, v244
	v_mov_b32_e32 v62, v245
	v_mov_b32_e32 v115, v246
	v_mov_b32_e32 v114, v247
	global_load_dword v232, v[6:7], off offset:12
	global_load_dword v233, v[8:9], off offset:2060
	global_load_dword v234, v[10:11], off offset:12
	global_load_dword v235, v[16:17], off offset:12
	global_load_dword v236, v[20:21], off offset:3084
	global_load_dword v237, v[18:19], off offset:3084
	global_load_dword v238, v[22:23], off offset:1036
	global_load_dword v239, v[24:25], off offset:3084
	v_mov_b32_dpp v111, v160 row_ror:1 row_mask:0xf bank_mask:0xf
	v_mov_b32_dpp v121, v160 row_ror:2 row_mask:0xf bank_mask:0xf
	v_cndmask_b32_e64 v161, v111, 0, s[38:39]
	v_cndmask_b32_e64 v82, 0, v121, s[40:41]
	v_mov_b32_dpp v123, v162 row_ror:1 row_mask:0xf bank_mask:0xf
	v_cndmask_b32_e64 v163, v123, 0, s[38:39]
	v_mov_b32_dpp v125, v162 row_ror:2 row_mask:0xf bank_mask:0xf
	v_cndmask_b32_e64 v99, 0, v125, s[40:41]
	s_nop 0
	v_fma_f32 v132, v63, v82, v75
	v_pk_mul_f32 v[82:83], v[58:59], v[160:161]
	s_nop 0
	v_fma_f32 v99, v62, v99, v74
	v_add_f32_e32 v83, v83, v132
	v_add_f32_e32 v135, v82, v83
	v_mul_f32_e32 v82, 0xbfb8aa3b, v135
	v_exp_f32_e32 v153, v82
	v_mov_b32_e32 v83, v58
	s_nop 0
	v_pk_mul_f32 v[132:133], v[114:115], v[162:163]
	v_mov_b32_e32 v82, v114
	v_add_f32_e32 v58, 1.0, v153
	v_rcp_f32_e32 v114, v58
	v_add_f32_e32 v99, v133, v99
	v_add_f32_e32 v99, v132, v99
	v_mov_b32_e32 v58, v115
	v_mul_f32_e32 v114, v135, v114
	v_mul_f32_e32 v99, v99, v114
	v_mov_b32_dpp v129, v175 row_ror:2 row_mask:0xf bank_mask:0xf
	v_mov_b32_dpp v134, v174 row_ror:2 row_mask:0xf bank_mask:0xf
	v_mov_b32_dpp v127, v175 row_ror:1 row_mask:0xf bank_mask:0xf
	v_mov_b32_dpp v131, v174 row_ror:1 row_mask:0xf bank_mask:0xf
	v_cndmask_b32_e64 v133, v121, v129, s[40:41]
	v_cndmask_b32_e64 v132, v125, v134, s[40:41]
	v_cndmask_b32_e64 v115, v127, v111, s[38:39]
	v_cndmask_b32_e64 v114, v131, v123, s[38:39]
	v_pk_fma_f32 v[132:133], v[62:63], v[132:133], v[74:75]
	v_pk_fma_f32 v[114:115], v[58:59], v[114:115], v[132:133]
	v_pk_fma_f32 v[114:115], v[82:83], v[174:175], v[114:115]
	v_mul_f32_e32 v111, 0xbfb8aa3b, v115
	v_exp_f32_e32 v111, v111
	s_nop 0
	v_add_f32_e32 v111, 1.0, v111
	v_rcp_f32_e32 v111, v111
	s_nop 0
	v_mul_f32_e32 v111, v115, v111
	v_mul_f32_e32 v114, v114, v111
	v_mov_b32_dpp v123, v105 row_ror:2 row_mask:0xf bank_mask:0xf
	v_mov_b32_dpp v153, v104 row_ror:2 row_mask:0xf bank_mask:0xf
	v_mov_b32_dpp v121, v105 row_ror:1 row_mask:0xf bank_mask:0xf
	v_mov_b32_dpp v125, v104 row_ror:1 row_mask:0xf bank_mask:0xf
	v_cndmask_b32_e64 v135, v129, v123, s[40:41]
	v_cndmask_b32_e64 v134, v134, v153, s[40:41]
	v_cndmask_b32_e64 v133, v121, v127, s[38:39]
	v_cndmask_b32_e64 v132, v125, v131, s[38:39]
	v_pk_fma_f32 v[134:135], v[62:63], v[134:135], v[74:75]
	v_pk_fma_f32 v[132:133], v[58:59], v[132:133], v[134:135]
	v_pk_fma_f32 v[104:105], v[82:83], v[104:105], v[132:133]
	v_mul_f32_e32 v111, 0xbfb8aa3b, v105
	v_exp_f32_e32 v111, v111
	s_nop 0
	v_add_f32_e32 v111, 1.0, v111
	v_rcp_f32_e32 v111, v111
	s_nop 0
	v_mul_f32_e32 v105, v105, v111
	v_mul_f32_e32 v104, v104, v105
	v_mov_b32_dpp v127, v89 row_ror:2 row_mask:0xf bank_mask:0xf
	v_mov_b32_dpp v131, v88 row_ror:2 row_mask:0xf bank_mask:0xf
	v_mov_b32_dpp v115, v89 row_ror:1 row_mask:0xf bank_mask:0xf
	v_mov_b32_dpp v129, v88 row_ror:1 row_mask:0xf bank_mask:0xf
	v_cndmask_b32_e64 v135, v123, v127, s[40:41]
	v_cndmask_b32_e64 v134, v153, v131, s[40:41]
	v_cndmask_b32_e64 v133, v115, v121, s[38:39]
	v_cndmask_b32_e64 v132, v129, v125, s[38:39]
	v_pk_fma_f32 v[134:135], v[62:63], v[134:135], v[74:75]
	v_pk_fma_f32 v[132:133], v[58:59], v[132:133], v[134:135]
	v_pk_fma_f32 v[88:89], v[82:83], v[88:89], v[132:133]
	v_mul_f32_e32 v105, 0xbfb8aa3b, v89
	v_exp_f32_e32 v105, v105
	s_nop 0
	v_add_f32_e32 v105, 1.0, v105
	v_rcp_f32_e32 v105, v105
	s_nop 0
	v_mul_f32_e32 v89, v89, v105
	v_mul_f32_e32 v88, v88, v89
; __device__ __forceinline__ float sigmoidf_(float x) { return __builtin_amdgcn_rcpf(1.0f + __expf(-x)); }
; template <int N> __device__ __forceinline__ float dpp_ror(float v) { return __builtin_bit_cast(float, __builtin_amdgcn_update_dpp(0, __builtin_bit_cast(int, v), 0x120 + N, 0xf, 0xf, false)); }
;     __device__ __forceinline__ void operator()(Acc& acc, const Unit& u, int wr, int wc, int fr, int fq) const {
;     ...
;         for (int n = 0; n < 2; ++n) {
; #pragma unroll
;             for (int i = 0; i < 4; ++i) {
;                 const int cg_ = ch0 + 4 * n + i, cv_ = DFF + cg_;
;                 const float g0 = cw[cg_], g1 = cw[NUP + cg_], g2 = cw[2 * NUP + cg_], gb = cb[cg_];
;                 const float v0 = cw[cv_], v1 = cw[NUP + cv_], v2 = cw[2 * NUP + cv_], vb = cb[cv_];
;                 float pg1 = 0.f, pg2 = 0.f, pv1 = 0.f, pv2 = 0.f;
; #pragma unroll
;                 for (int q = 0; q < 8; ++q) {
;                     float cgv = acc[q >> 2][0][q & 3][n][i], cvv = acc[q >> 2][1][q & 3][n][i];
;                     asm volatile("" : "+v"(cgv), "+v"(cvv) : "v"(chain));
;                     const float tg1 = dpp_ror<1>(cgv), tg2 = dpp_ror<2>(cgv), tv1 = dpp_ror<1>(cvv), tv2 = dpp_ror<2>(cvv);
;                     const float sg1 = fr >= 1 ? tg1 : pg1, sg2 = fr >= 2 ? tg2 : pg2, sv1 = fr >= 1 ? tv1 : pv1, sv2 = fr >= 2 ? tv2 : pv2;
;                     const float gg = gb + g0 * sg2 + g1 * sg1 + g2 * cgv;
;                     const float vv = vb + v0 * sv2 + v1 * sv1 + v2 * cvv;
;                     chain = gg * sigmoidf_(gg) * vv; acc[q >> 2][0][q & 3][n][i] = chain;
;                     pg1 = tg1; pg2 = tg2; pv1 = tv1; pv2 = tv2;
;                 }
;                 __builtin_amdgcn_sched_barrier(0);
;             }
;         }
	v_mov_b32_dpp v121, v73 row_ror:2 row_mask:0xf bank_mask:0xf
	v_mov_b32_dpp v125, v72 row_ror:2 row_mask:0xf bank_mask:0xf
	v_mov_b32_dpp v111, v73 row_ror:1 row_mask:0xf bank_mask:0xf
	v_mov_b32_dpp v123, v72 row_ror:1 row_mask:0xf bank_mask:0xf
	v_cndmask_b32_e64 v135, v127, v121, s[40:41]
	v_cndmask_b32_e64 v134, v131, v125, s[40:41]
	v_cndmask_b32_e64 v133, v111, v115, s[38:39]
	v_cndmask_b32_e64 v132, v123, v129, s[38:39]
	v_pk_fma_f32 v[134:135], v[62:63], v[134:135], v[74:75]
	v_pk_fma_f32 v[132:133], v[58:59], v[132:133], v[134:135]
	v_pk_fma_f32 v[72:73], v[82:83], v[72:73], v[132:133]
	v_mul_f32_e32 v89, 0xbfb8aa3b, v73
	v_exp_f32_e32 v89, v89
	s_nop 0
	v_add_f32_e32 v89, 1.0, v89
	v_rcp_f32_e32 v89, v89
	s_nop 0
	v_mul_f32_e32 v73, v73, v89
	v_mul_f32_e32 v72, v72, v73
	v_mov_b32_dpp v115, v57 row_ror:2 row_mask:0xf bank_mask:0xf
	v_mov_b32_dpp v129, v56 row_ror:2 row_mask:0xf bank_mask:0xf
	v_mov_b32_dpp v105, v57 row_ror:1 row_mask:0xf bank_mask:0xf
	v_mov_b32_dpp v127, v56 row_ror:1 row_mask:0xf bank_mask:0xf
	v_cndmask_b32_e64 v135, v121, v115, s[40:41]
	v_cndmask_b32_e64 v134, v125, v129, s[40:41]
	v_cndmask_b32_e64 v133, v105, v111, s[38:39]
	v_cndmask_b32_e64 v132, v127, v123, s[38:39]
	v_pk_fma_f32 v[134:135], v[62:63], v[134:135], v[74:75]
	v_pk_fma_f32 v[132:133], v[58:59], v[132:133], v[134:135]
	v_pk_fma_f32 v[56:57], v[82:83], v[56:57], v[132:133]
	v_mul_f32_e32 v73, 0xbfb8aa3b, v57
	v_exp_f32_e32 v73, v73
	s_nop 0
	v_add_f32_e32 v73, 1.0, v73
	v_rcp_f32_e32 v73, v73
	s_nop 0
	v_mul_f32_e32 v57, v57, v73
	v_mul_f32_e32 v73, v56, v57
	v_mov_b32_dpp v121, v43 row_ror:2 row_mask:0xf bank_mask:0xf
	v_mov_b32_dpp v125, v42 row_ror:2 row_mask:0xf bank_mask:0xf
	v_mov_b32_dpp v111, v43 row_ror:1 row_mask:0xf bank_mask:0xf
	v_mov_b32_dpp v123, v42 row_ror:1 row_mask:0xf bank_mask:0xf
	v_cndmask_b32_e64 v133, v115, v121, s[40:41]
	v_cndmask_b32_e64 v132, v129, v125, s[40:41]
	v_cndmask_b32_e64 v57, v111, v105, s[38:39]
	v_cndmask_b32_e64 v56, v123, v127, s[38:39]
	v_pk_fma_f32 v[132:133], v[62:63], v[132:133], v[74:75]
	v_pk_fma_f32 v[56:57], v[58:59], v[56:57], v[132:133]
	v_pk_fma_f32 v[42:43], v[82:83], v[42:43], v[56:57]
	v_mul_f32_e32 v56, 0xbfb8aa3b, v43
	v_exp_f32_e32 v56, v56
	s_nop 0
	v_add_f32_e32 v56, 1.0, v56
	v_rcp_f32_e32 v56, v56
	s_nop 0
	v_mul_f32_e32 v43, v43, v56
	v_mul_f32_e32 v89, v42, v43
	v_mov_b32_dpp v57, v51 row_ror:1 row_mask:0xf bank_mask:0xf
	v_mov_b32_dpp v105, v51 row_ror:2 row_mask:0xf bank_mask:0xf
	v_mov_b32_dpp v127, v50 row_ror:2 row_mask:0xf bank_mask:0xf
	v_mov_b32_dpp v115, v50 row_ror:1 row_mask:0xf bank_mask:0xf
	v_cndmask_b32_e64 v43, v57, v111, s[38:39]
	v_cndmask_b32_e64 v57, v121, v105, s[40:41]
	v_cndmask_b32_e64 v56, v125, v127, s[40:41]
	v_cndmask_b32_e64 v42, v115, v123, s[38:39]
	v_pk_fma_f32 v[56:57], v[62:63], v[56:57], v[74:75]
	s_nop 0
	v_pk_fma_f32 v[42:43], v[58:59], v[42:43], v[56:57]
	s_nop 0
	v_pk_fma_f32 v[42:43], v[82:83], v[50:51], v[42:43]
	s_nop 0
	v_mul_f32_e32 v50, 0xbfb8aa3b, v43
	v_exp_f32_e32 v50, v50
	s_nop 0
	v_add_f32_e32 v50, 1.0, v50
	v_rcp_f32_e32 v50, v50
	s_nop 0
	v_mul_f32_e32 v43, v43, v50
	v_mul_f32_e32 v62, v42, v43
	s_waitcnt vmcnt(0)
	v_mov_b32_e32 v51, v232
	v_mov_b32_e32 v43, v233
	v_mov_b32_e32 v42, v234
	v_mov_b32_e32 v57, v235
	v_mov_b32_e32 v56, v236
	v_mov_b32_e32 v50, v237
	v_mov_b32_e32 v75, v238
	v_mov_b32_e32 v74, v239
	global_load_dword v240, v[6:7], off offset:16
	global_load_dword v241, v[8:9], off offset:2064
	global_load_dword v242, v[10:11], off offset:16
	global_load_dword v243, v[16:17], off offset:16
	global_load_dword v244, v[20:21], off offset:3088
	global_load_dword v245, v[18:19], off offset:3088
	global_load_dword v246, v[22:23], off offset:1040
	global_load_dword v247, v[24:25], off offset:3088
	v_mov_b32_dpp v105, v154 row_ror:1 row_mask:0xf bank_mask:0xf
	v_mov_b32_dpp v111, v154 row_ror:2 row_mask:0xf bank_mask:0xf
	v_cndmask_b32_e64 v155, v105, 0, s[38:39]
	v_cndmask_b32_e64 v58, 0, v111, s[40:41]
	v_mov_b32_dpp v115, v158 row_ror:1 row_mask:0xf bank_mask:0xf
	v_cndmask_b32_e64 v159, v115, 0, s[38:39]
	v_mov_b32_dpp v121, v158 row_ror:2 row_mask:0xf bank_mask:0xf
	v_cndmask_b32_e64 v63, 0, v121, s[40:41]
	s_nop 0
	v_fma_f32 v82, v51, v58, v57
	v_pk_mul_f32 v[58:59], v[42:43], v[154:155]
	s_nop 0
	v_fma_f32 v63, v50, v63, v56
	v_add_f32_e32 v59, v59, v82
	v_add_f32_e32 v131, v58, v59
	v_mul_f32_e32 v58, 0xbfb8aa3b, v131
	v_exp_f32_e32 v132, v58
	v_mov_b32_e32 v59, v42
	s_nop 0
	v_pk_mul_f32 v[82:83], v[74:75], v[158:159]
	v_mov_b32_e32 v58, v74
	v_add_f32_e32 v42, 1.0, v132
	v_rcp_f32_e32 v74, v42
	v_add_f32_e32 v63, v83, v63
	v_add_f32_e32 v63, v82, v63
	v_mov_b32_e32 v42, v75
	v_mul_f32_e32 v74, v131, v74
	v_mul_f32_e32 v63, v63, v74
	v_mov_b32_dpp v125, v157 row_ror:2 row_mask:0xf bank_mask:0xf
	v_mov_b32_dpp v129, v156 row_ror:2 row_mask:0xf bank_mask:0xf
	v_mov_b32_dpp v123, v157 row_ror:1 row_mask:0xf bank_mask:0xf
	v_mov_b32_dpp v127, v156 row_ror:1 row_mask:0xf bank_mask:0xf
	v_cndmask_b32_e64 v83, v111, v125, s[40:41]
	v_cndmask_b32_e64 v82, v121, v129, s[40:41]
	v_cndmask_b32_e64 v75, v123, v105, s[38:39]
	v_cndmask_b32_e64 v74, v127, v115, s[38:39]
	v_pk_fma_f32 v[82:83], v[50:51], v[82:83], v[56:57]
	v_pk_fma_f32 v[74:75], v[42:43], v[74:75], v[82:83]
	v_pk_fma_f32 v[74:75], v[58:59], v[156:157], v[74:75]
	v_mul_f32_e32 v82, 0xbfb8aa3b, v75
	v_exp_f32_e32 v82, v82
	s_nop 0
	v_add_f32_e32 v82, 1.0, v82
	v_rcp_f32_e32 v82, v82
	s_nop 0
	v_mul_f32_e32 v75, v75, v82
	v_mul_f32_e32 v74, v74, v75
	v_mov_b32_dpp v111, v103 row_ror:2 row_mask:0xf bank_mask:0xf
	v_mov_b32_dpp v121, v102 row_ror:2 row_mask:0xf bank_mask:0xf
; __device__ __forceinline__ float sigmoidf_(float x) { return __builtin_amdgcn_rcpf(1.0f + __expf(-x)); }
; template <int N> __device__ __forceinline__ float dpp_ror(float v) { return __builtin_bit_cast(float, __builtin_amdgcn_update_dpp(0, __builtin_bit_cast(int, v), 0x120 + N, 0xf, 0xf, false)); }
;     __device__ __forceinline__ void operator()(Acc& acc, const Unit& u, int wr, int wc, int fr, int fq) const {
;     ...
;         for (int n = 0; n < 2; ++n) {
; #pragma unroll
;             for (int i = 0; i < 4; ++i) {
;                 const int cg_ = ch0 + 4 * n + i, cv_ = DFF + cg_;
;                 const float g0 = cw[cg_], g1 = cw[NUP + cg_], g2 = cw[2 * NUP + cg_], gb = cb[cg_];
;                 const float v0 = cw[cv_], v1 = cw[NUP + cv_], v2 = cw[2 * NUP + cv_], vb = cb[cv_];
;                 float pg1 = 0.f, pg2 = 0.f, pv1 = 0.f, pv2 = 0.f;
; #pragma unroll
;                 for (int q = 0; q < 8; ++q) {
;                     float cgv = acc[q >> 2][0][q & 3][n][i], cvv = acc[q >> 2][1][q & 3][n][i];
;                     asm volatile("" : "+v"(cgv), "+v"(cvv) : "v"(chain));
;                     const float tg1 = dpp_ror<1>(cgv), tg2 = dpp_ror<2>(cgv), tv1 = dpp_ror<1>(cvv), tv2 = dpp_ror<2>(cvv);
;                     const float sg1 = fr >= 1 ? tg1 : pg1, sg2 = fr >= 2 ? tg2 : pg2, sv1 = fr >= 1 ? tv1 : pv1, sv2 = fr >= 2 ? tv2 : pv2;
;                     const float gg = gb + g0 * sg2 + g1 * sg1 + g2 * cgv;
;                     const float vv = vb + v0 * sv2 + v1 * sv1 + v2 * cvv;
;                     chain = gg * sigmoidf_(gg) * vv; acc[q >> 2][0][q & 3][n][i] = chain;
;                     pg1 = tg1; pg2 = tg2; pv1 = tv1; pv2 = tv2;
;                 }
;                 __builtin_amdgcn_sched_barrier(0);
;             }
;         }
	v_mov_b32_dpp v105, v103 row_ror:1 row_mask:0xf bank_mask:0xf
	v_mov_b32_dpp v115, v102 row_ror:1 row_mask:0xf bank_mask:0xf
	v_cndmask_b32_e64 v133, v125, v111, s[40:41]
	v_cndmask_b32_e64 v132, v129, v121, s[40:41]
	v_cndmask_b32_e64 v83, v105, v123, s[38:39]
	v_cndmask_b32_e64 v82, v115, v127, s[38:39]
	v_pk_fma_f32 v[132:133], v[50:51], v[132:133], v[56:57]
	v_pk_fma_f32 v[82:83], v[42:43], v[82:83], v[132:133]
	v_pk_fma_f32 v[82:83], v[58:59], v[102:103], v[82:83]
	v_mul_f32_e32 v75, 0xbfb8aa3b, v83
	v_exp_f32_e32 v75, v75
	s_nop 0
	v_add_f32_e32 v75, 1.0, v75
	v_rcp_f32_e32 v75, v75
	s_nop 0
	v_mul_f32_e32 v75, v83, v75
	v_mul_f32_e32 v75, v82, v75
	v_mov_b32_dpp v125, v87 row_ror:2 row_mask:0xf bank_mask:0xf
	v_mov_b32_dpp v129, v86 row_ror:2 row_mask:0xf bank_mask:0xf
	v_mov_b32_dpp v123, v87 row_ror:1 row_mask:0xf bank_mask:0xf
	v_mov_b32_dpp v127, v86 row_ror:1 row_mask:0xf bank_mask:0xf
	v_cndmask_b32_e64 v103, v111, v125, s[40:41]
	v_cndmask_b32_e64 v102, v121, v129, s[40:41]
	v_cndmask_b32_e64 v83, v123, v105, s[38:39]
	v_cndmask_b32_e64 v82, v127, v115, s[38:39]
	v_pk_fma_f32 v[102:103], v[50:51], v[102:103], v[56:57]
	v_pk_fma_f32 v[82:83], v[42:43], v[82:83], v[102:103]
	v_pk_fma_f32 v[82:83], v[58:59], v[86:87], v[82:83]
	v_mul_f32_e32 v86, 0xbfb8aa3b, v83
	v_exp_f32_e32 v86, v86
	s_nop 0
	v_add_f32_e32 v86, 1.0, v86
	v_rcp_f32_e32 v86, v86
	s_nop 0
	v_mul_f32_e32 v83, v83, v86
	v_mul_f32_e32 v82, v82, v83
	v_mov_b32_dpp v111, v71 row_ror:2 row_mask:0xf bank_mask:0xf
	v_mov_b32_dpp v121, v70 row_ror:2 row_mask:0xf bank_mask:0xf
	v_mov_b32_dpp v105, v71 row_ror:1 row_mask:0xf bank_mask:0xf
	v_mov_b32_dpp v115, v70 row_ror:1 row_mask:0xf bank_mask:0xf
	v_cndmask_b32_e64 v103, v125, v111, s[40:41]
	v_cndmask_b32_e64 v102, v129, v121, s[40:41]
	v_cndmask_b32_e64 v87, v105, v123, s[38:39]
	v_cndmask_b32_e64 v86, v115, v127, s[38:39]
	v_pk_fma_f32 v[102:103], v[50:51], v[102:103], v[56:57]
	v_pk_fma_f32 v[86:87], v[42:43], v[86:87], v[102:103]
	v_pk_fma_f32 v[70:71], v[58:59], v[70:71], v[86:87]
	v_mul_f32_e32 v83, 0xbfb8aa3b, v71
	v_exp_f32_e32 v83, v83
	s_nop 0
	v_add_f32_e32 v83, 1.0, v83
	v_rcp_f32_e32 v83, v83
	s_nop 0
	v_mul_f32_e32 v71, v71, v83
	v_mul_f32_e32 v70, v70, v71
	v_mov_b32_dpp v125, v55 row_ror:2 row_mask:0xf bank_mask:0xf
	v_mov_b32_dpp v129, v54 row_ror:2 row_mask:0xf bank_mask:0xf
	v_mov_b32_dpp v123, v55 row_ror:1 row_mask:0xf bank_mask:0xf
	v_mov_b32_dpp v127, v54 row_ror:1 row_mask:0xf bank_mask:0xf
	v_cndmask_b32_e64 v103, v111, v125, s[40:41]
	v_cndmask_b32_e64 v102, v121, v129, s[40:41]
	v_cndmask_b32_e64 v87, v123, v105, s[38:39]
	v_cndmask_b32_e64 v86, v127, v115, s[38:39]
	v_pk_fma_f32 v[102:103], v[50:51], v[102:103], v[56:57]
	v_pk_fma_f32 v[86:87], v[42:43], v[86:87], v[102:103]
	v_pk_fma_f32 v[54:55], v[58:59], v[54:55], v[86:87]
	v_mul_f32_e32 v71, 0xbfb8aa3b, v55
	v_exp_f32_e32 v71, v71
	s_nop 0
	v_add_f32_e32 v71, 1.0, v71
	v_rcp_f32_e32 v71, v71
	s_nop 0
	v_mul_f32_e32 v55, v55, v71
	v_mul_f32_e32 v55, v54, v55
	v_mov_b32_dpp v105, v39 row_ror:2 row_mask:0xf bank_mask:0xf
	v_mov_b32_dpp v115, v38 row_ror:2 row_mask:0xf bank_mask:0xf
	v_mov_b32_dpp v83, v39 row_ror:1 row_mask:0xf bank_mask:0xf
	v_mov_b32_dpp v111, v38 row_ror:1 row_mask:0xf bank_mask:0xf
	v_cndmask_b32_e64 v103, v125, v105, s[40:41]
	v_cndmask_b32_e64 v102, v129, v115, s[40:41]
	v_cndmask_b32_e64 v87, v83, v123, s[38:39]
	v_cndmask_b32_e64 v86, v111, v127, s[38:39]
	v_pk_fma_f32 v[102:103], v[50:51], v[102:103], v[56:57]
	s_nop 0
	v_pk_fma_f32 v[86:87], v[42:43], v[86:87], v[102:103]
	v_pk_fma_f32 v[38:39], v[58:59], v[38:39], v[86:87]
	v_mul_f32_e32 v54, 0xbfb8aa3b, v39
	v_exp_f32_e32 v54, v54
	s_nop 0
	v_add_f32_e32 v54, 1.0, v54
	v_rcp_f32_e32 v54, v54
	s_nop 0
	v_mul_f32_e32 v39, v39, v54
	v_mul_f32_e32 v71, v38, v39
	v_mov_b32_dpp v86, v41 row_ror:1 row_mask:0xf bank_mask:0xf
	v_mov_b32_dpp v87, v41 row_ror:2 row_mask:0xf bank_mask:0xf
	v_mov_b32_dpp v103, v40 row_ror:2 row_mask:0xf bank_mask:0xf
	v_mov_b32_dpp v102, v40 row_ror:1 row_mask:0xf bank_mask:0xf
	v_cndmask_b32_e64 v39, v86, v83, s[38:39]
	v_cndmask_b32_e64 v87, v105, v87, s[40:41]
	v_cndmask_b32_e64 v86, v115, v103, s[40:41]
	v_cndmask_b32_e64 v38, v102, v111, s[38:39]
	v_pk_fma_f32 v[50:51], v[50:51], v[86:87], v[56:57]
	s_nop 0
	v_pk_fma_f32 v[38:39], v[42:43], v[38:39], v[50:51]
	s_nop 0
	v_pk_fma_f32 v[38:39], v[58:59], v[40:41], v[38:39]
	s_nop 0
	v_mul_f32_e32 v40, 0xbfb8aa3b, v39
	v_exp_f32_e32 v40, v40
	s_nop 0
	v_add_f32_e32 v40, 1.0, v40
	v_rcp_f32_e32 v40, v40
	s_nop 0
	v_mul_f32_e32 v39, v39, v40
	v_mul_f32_e32 v54, v38, v39
	s_waitcnt vmcnt(0)
; __device__ __forceinline__ float sigmoidf_(float x) { return __builtin_amdgcn_rcpf(1.0f + __expf(-x)); }
; template <int N> __device__ __forceinline__ float dpp_ror(float v) { return __builtin_bit_cast(float, __builtin_amdgcn_update_dpp(0, __builtin_bit_cast(int, v), 0x120 + N, 0xf, 0xf, false)); }
;     __device__ __forceinline__ void operator()(Acc& acc, const Unit& u, int wr, int wc, int fr, int fq) const {
;     ...
;         for (int n = 0; n < 2; ++n) {
; #pragma unroll
;             for (int i = 0; i < 4; ++i) {
;                 const int cg_ = ch0 + 4 * n + i, cv_ = DFF + cg_;
;                 const float g0 = cw[cg_], g1 = cw[NUP + cg_], g2 = cw[2 * NUP + cg_], gb = cb[cg_];
;                 const float v0 = cw[cv_], v1 = cw[NUP + cv_], v2 = cw[2 * NUP + cv_], vb = cb[cv_];
;                 float pg1 = 0.f, pg2 = 0.f, pv1 = 0.f, pv2 = 0.f;
; #pragma unroll
;                 for (int q = 0; q < 8; ++q) {
;                     float cgv = acc[q >> 2][0][q & 3][n][i], cvv = acc[q >> 2][1][q & 3][n][i];
;                     asm volatile("" : "+v"(cgv), "+v"(cvv) : "v"(chain));
;                     const float tg1 = dpp_ror<1>(cgv), tg2 = dpp_ror<2>(cgv), tv1 = dpp_ror<1>(cvv), tv2 = dpp_ror<2>(cvv);
;                     const float sg1 = fr >= 1 ? tg1 : pg1, sg2 = fr >= 2 ? tg2 : pg2, sv1 = fr >= 1 ? tv1 : pv1, sv2 = fr >= 2 ? tv2 : pv2;
;                     const float gg = gb + g0 * sg2 + g1 * sg1 + g2 * cgv;
;                     const float vv = vb + v0 * sv2 + v1 * sv1 + v2 * cvv;
;                     chain = gg * sigmoidf_(gg) * vv; acc[q >> 2][0][q & 3][n][i] = chain;
;                     pg1 = tg1; pg2 = tg2; pv1 = tv1; pv2 = tv2;
;                 }
;                 __builtin_amdgcn_sched_barrier(0);
;             }
;         }
	v_mov_b32_e32 v41, v240
	v_mov_b32_e32 v39, v241
	v_mov_b32_e32 v38, v242
	v_mov_b32_e32 v43, v243
	v_mov_b32_e32 v42, v244
	v_mov_b32_e32 v40, v245
	v_mov_b32_e32 v57, v246
	v_mov_b32_e32 v56, v247
	global_load_dword v232, v[6:7], off offset:20
	global_load_dword v233, v[8:9], off offset:2068
	global_load_dword v234, v[10:11], off offset:20
	global_load_dword v235, v[16:17], off offset:20
	global_load_dword v236, v[20:21], off offset:3092
	global_load_dword v237, v[18:19], off offset:3092
	global_load_dword v238, v[22:23], off offset:1044
	global_load_dword v239, v[24:25], off offset:3092
	v_mov_b32_dpp v83, v130 row_ror:1 row_mask:0xf bank_mask:0xf
	v_mov_b32_dpp v86, v130 row_ror:2 row_mask:0xf bank_mask:0xf
	v_cndmask_b32_e64 v131, v83, 0, s[38:39]
	v_cndmask_b32_e64 v50, 0, v86, s[40:41]
	v_mov_b32_dpp v87, v152 row_ror:1 row_mask:0xf bank_mask:0xf
	v_mov_b32_dpp v102, v152 row_ror:2 row_mask:0xf bank_mask:0xf
	v_cndmask_b32_e64 v153, v87, 0, s[38:39]
	v_cndmask_b32_e64 v58, 0, v102, s[40:41]
	s_nop 0
	v_fma_f32 v59, v41, v50, v43
	v_pk_mul_f32 v[50:51], v[38:39], v[130:131]
	s_nop 0
	v_fma_f32 v121, v40, v58, v42
	v_add_f32_e32 v51, v51, v59
	v_add_f32_e32 v123, v50, v51
	v_mul_f32_e32 v50, 0xbfb8aa3b, v123
	v_exp_f32_e32 v125, v50
	v_mov_b32_e32 v51, v38
	s_nop 0
	v_pk_mul_f32 v[58:59], v[56:57], v[152:153]
	v_mov_b32_e32 v50, v56
	v_add_f32_e32 v38, 1.0, v125
	v_rcp_f32_e32 v56, v38
	v_mov_b32_e32 v38, v57
	v_add_f32_e32 v57, v59, v121
	v_add_f32_e32 v57, v58, v57
	v_mul_f32_e32 v56, v123, v56
	v_mul_f32_e32 v56, v57, v56
	v_mov_b32_dpp v105, v119 row_ror:2 row_mask:0xf bank_mask:0xf
	v_mov_b32_dpp v111, v118 row_ror:1 row_mask:0xf bank_mask:0xf
	v_mov_b32_dpp v115, v118 row_ror:2 row_mask:0xf bank_mask:0xf
	v_mov_b32_dpp v103, v119 row_ror:1 row_mask:0xf bank_mask:0xf
	v_cndmask_b32_e64 v58, v111, v87, s[38:39]
	v_cndmask_b32_e64 v87, v86, v105, s[40:41]
	v_cndmask_b32_e64 v86, v102, v115, s[40:41]
	v_cndmask_b32_e64 v59, v103, v83, s[38:39]
	v_pk_fma_f32 v[86:87], v[40:41], v[86:87], v[42:43]
	v_pk_fma_f32 v[58:59], v[38:39], v[58:59], v[86:87]
	v_pk_fma_f32 v[58:59], v[50:51], v[118:119], v[58:59]
	v_mul_f32_e32 v57, 0xbfb8aa3b, v59
	v_exp_f32_e32 v57, v57
	s_nop 0
	v_add_f32_e32 v57, 1.0, v57
	v_rcp_f32_e32 v57, v57
	s_nop 0
	v_mul_f32_e32 v57, v59, v57
	v_mul_f32_e32 v57, v58, v57
	v_mov_b32_dpp v102, v101 row_ror:2 row_mask:0xf bank_mask:0xf
	v_mov_b32_dpp v119, v100 row_ror:2 row_mask:0xf bank_mask:0xf
	v_mov_b32_dpp v83, v101 row_ror:1 row_mask:0xf bank_mask:0xf
	v_mov_b32_dpp v118, v100 row_ror:1 row_mask:0xf bank_mask:0xf
	v_cndmask_b32_e64 v87, v105, v102, s[40:41]
	v_cndmask_b32_e64 v86, v115, v119, s[40:41]
	v_cndmask_b32_e64 v59, v83, v103, s[38:39]
	v_cndmask_b32_e64 v58, v118, v111, s[38:39]
	v_pk_fma_f32 v[86:87], v[40:41], v[86:87], v[42:43]
	v_pk_fma_f32 v[58:59], v[38:39], v[58:59], v[86:87]
	v_pk_fma_f32 v[58:59], v[50:51], v[100:101], v[58:59]
	v_mul_f32_e32 v86, 0xbfb8aa3b, v59
	v_exp_f32_e32 v86, v86
	s_nop 0
	v_add_f32_e32 v86, 1.0, v86
	v_rcp_f32_e32 v86, v86
	s_nop 0
	v_mul_f32_e32 v59, v59, v86
	v_mul_f32_e32 v58, v58, v59
	v_mov_b32_dpp v105, v85 row_ror:2 row_mask:0xf bank_mask:0xf
	v_mov_b32_dpp v115, v84 row_ror:2 row_mask:0xf bank_mask:0xf
	v_mov_b32_dpp v103, v85 row_ror:1 row_mask:0xf bank_mask:0xf
	v_mov_b32_dpp v111, v84 row_ror:1 row_mask:0xf bank_mask:0xf
	v_cndmask_b32_e64 v101, v102, v105, s[40:41]
	v_cndmask_b32_e64 v100, v119, v115, s[40:41]
	v_cndmask_b32_e64 v87, v103, v83, s[38:39]
	v_cndmask_b32_e64 v86, v111, v118, s[38:39]
	v_pk_fma_f32 v[100:101], v[40:41], v[100:101], v[42:43]
	v_pk_fma_f32 v[86:87], v[38:39], v[86:87], v[100:101]
	v_pk_fma_f32 v[84:85], v[50:51], v[84:85], v[86:87]
	v_mul_f32_e32 v59, 0xbfb8aa3b, v85
	v_exp_f32_e32 v59, v59
	s_nop 0
	v_add_f32_e32 v59, 1.0, v59
	v_rcp_f32_e32 v59, v59
	s_nop 0
	v_mul_f32_e32 v59, v85, v59
	v_mul_f32_e32 v59, v84, v59
	v_mov_b32_dpp v100, v69 row_ror:2 row_mask:0xf bank_mask:0xf
	v_mov_b32_dpp v102, v68 row_ror:2 row_mask:0xf bank_mask:0xf
	v_mov_b32_dpp v83, v69 row_ror:1 row_mask:0xf bank_mask:0xf
	v_mov_b32_dpp v101, v68 row_ror:1 row_mask:0xf bank_mask:0xf
	v_cndmask_b32_e64 v87, v105, v100, s[40:41]
	v_cndmask_b32_e64 v86, v115, v102, s[40:41]
	v_cndmask_b32_e64 v85, v83, v103, s[38:39]
	v_cndmask_b32_e64 v84, v101, v111, s[38:39]
	v_pk_fma_f32 v[86:87], v[40:41], v[86:87], v[42:43]
	v_pk_fma_f32 v[84:85], v[38:39], v[84:85], v[86:87]
	v_pk_fma_f32 v[68:69], v[50:51], v[68:69], v[84:85]
	v_mul_f32_e32 v84, 0xbfb8aa3b, v69
	v_exp_f32_e32 v84, v84
	s_nop 0
	v_add_f32_e32 v84, 1.0, v84
	v_rcp_f32_e32 v84, v84
	s_nop 0
	v_mul_f32_e32 v69, v69, v84
	v_mul_f32_e32 v68, v68, v69
	v_mov_b32_dpp v105, v53 row_ror:2 row_mask:0xf bank_mask:0xf
	v_mov_b32_dpp v115, v52 row_ror:2 row_mask:0xf bank_mask:0xf
	v_mov_b32_dpp v103, v53 row_ror:1 row_mask:0xf bank_mask:0xf
	v_mov_b32_dpp v111, v52 row_ror:1 row_mask:0xf bank_mask:0xf
	v_cndmask_b32_e64 v87, v100, v105, s[40:41]
	v_cndmask_b32_e64 v86, v102, v115, s[40:41]
	v_cndmask_b32_e64 v85, v103, v83, s[38:39]
	v_cndmask_b32_e64 v84, v111, v101, s[38:39]
	v_pk_fma_f32 v[86:87], v[40:41], v[86:87], v[42:43]
	v_pk_fma_f32 v[84:85], v[38:39], v[84:85], v[86:87]
	v_pk_fma_f32 v[52:53], v[50:51], v[52:53], v[84:85]
	v_mul_f32_e32 v69, 0xbfb8aa3b, v53
	v_exp_f32_e32 v69, v69
	s_nop 0
	v_add_f32_e32 v69, 1.0, v69
	v_rcp_f32_e32 v69, v69
	s_nop 0
	v_mul_f32_e32 v53, v53, v69
	v_mul_f32_e32 v52, v52, v53
	v_mov_b32_dpp v100, v37 row_ror:2 row_mask:0xf bank_mask:0xf
	v_mov_b32_dpp v102, v36 row_ror:2 row_mask:0xf bank_mask:0xf
	v_mov_b32_dpp v83, v37 row_ror:1 row_mask:0xf bank_mask:0xf
	v_mov_b32_dpp v101, v36 row_ror:1 row_mask:0xf bank_mask:0xf
	v_cndmask_b32_e64 v87, v105, v100, s[40:41]
	v_cndmask_b32_e64 v86, v115, v102, s[40:41]
	v_cndmask_b32_e64 v85, v83, v103, s[38:39]
	v_cndmask_b32_e64 v84, v101, v111, s[38:39]
	v_pk_fma_f32 v[86:87], v[40:41], v[86:87], v[42:43]
	s_nop 0
	v_pk_fma_f32 v[84:85], v[38:39], v[84:85], v[86:87]
	v_pk_fma_f32 v[36:37], v[50:51], v[36:37], v[84:85]
	v_mul_f32_e32 v53, 0xbfb8aa3b, v37
	v_exp_f32_e32 v53, v53
	s_nop 0
	v_add_f32_e32 v53, 1.0, v53
	v_rcp_f32_e32 v53, v53
	s_nop 0
	v_mul_f32_e32 v37, v37, v53
	v_mul_f32_e32 v53, v36, v37
	v_mov_b32_dpp v84, v35 row_ror:2 row_mask:0xf bank_mask:0xf
	v_mov_b32_dpp v85, v34 row_ror:1 row_mask:0xf bank_mask:0xf
	v_mov_b32_dpp v86, v34 row_ror:2 row_mask:0xf bank_mask:0xf
	v_mov_b32_dpp v69, v35 row_ror:1 row_mask:0xf bank_mask:0xf
	v_cndmask_b32_e64 v36, v85, v101, s[38:39]
	v_cndmask_b32_e64 v85, v100, v84, s[40:41]
	v_cndmask_b32_e64 v84, v102, v86, s[40:41]
	v_cndmask_b32_e64 v37, v69, v83, s[38:39]
	v_pk_fma_f32 v[40:41], v[40:41], v[84:85], v[42:43]
	s_nop 0
	v_pk_fma_f32 v[36:37], v[38:39], v[36:37], v[40:41]
	s_nop 0
	v_pk_fma_f32 v[34:35], v[50:51], v[34:35], v[36:37]
	s_nop 0
	v_mul_f32_e32 v36, 0xbfb8aa3b, v35
	v_exp_f32_e32 v36, v36
	s_nop 0
	v_add_f32_e32 v36, 1.0, v36
	v_rcp_f32_e32 v36, v36
	s_nop 0
	v_mul_f32_e32 v35, v35, v36
	v_mul_f32_e32 v42, v34, v35
	s_waitcnt vmcnt(0)
; __device__ __forceinline__ float sigmoidf_(float x) { return __builtin_amdgcn_rcpf(1.0f + __expf(-x)); }
; template <int N> __device__ __forceinline__ float dpp_ror(float v) { return __builtin_bit_cast(float, __builtin_amdgcn_update_dpp(0, __builtin_bit_cast(int, v), 0x120 + N, 0xf, 0xf, false)); }
;     __device__ __forceinline__ void operator()(Acc& acc, const Unit& u, int wr, int wc, int fr, int fq) const {
;     ...
;         for (int n = 0; n < 2; ++n) {
; #pragma unroll
;             for (int i = 0; i < 4; ++i) {
;                 const int cg_ = ch0 + 4 * n + i, cv_ = DFF + cg_;
;                 const float g0 = cw[cg_], g1 = cw[NUP + cg_], g2 = cw[2 * NUP + cg_], gb = cb[cg_];
;                 const float v0 = cw[cv_], v1 = cw[NUP + cv_], v2 = cw[2 * NUP + cv_], vb = cb[cv_];
;                 float pg1 = 0.f, pg2 = 0.f, pv1 = 0.f, pv2 = 0.f;
; #pragma unroll
;                 for (int q = 0; q < 8; ++q) {
;                     float cgv = acc[q >> 2][0][q & 3][n][i], cvv = acc[q >> 2][1][q & 3][n][i];
;                     asm volatile("" : "+v"(cgv), "+v"(cvv) : "v"(chain));
;                     const float tg1 = dpp_ror<1>(cgv), tg2 = dpp_ror<2>(cgv), tv1 = dpp_ror<1>(cvv), tv2 = dpp_ror<2>(cvv);
;                     const float sg1 = fr >= 1 ? tg1 : pg1, sg2 = fr >= 2 ? tg2 : pg2, sv1 = fr >= 1 ? tv1 : pv1, sv2 = fr >= 2 ? tv2 : pv2;
;                     const float gg = gb + g0 * sg2 + g1 * sg1 + g2 * cgv;
;                     const float vv = vb + v0 * sv2 + v1 * sv1 + v2 * cvv;
;                     chain = gg * sigmoidf_(gg) * vv; acc[q >> 2][0][q & 3][n][i] = chain;
;                     pg1 = tg1; pg2 = tg2; pv1 = tv1; pv2 = tv2;
;                 }
;                 __builtin_amdgcn_sched_barrier(0);
;             }
;         }
	v_mov_b32_e32 v37, v232
	v_mov_b32_e32 v35, v233
	v_mov_b32_e32 v34, v234
	v_mov_b32_e32 v39, v235
	v_mov_b32_e32 v38, v236
	v_mov_b32_e32 v36, v237
	v_mov_b32_e32 v51, v238
	v_mov_b32_e32 v50, v239
	global_load_dword v240, v[6:7], off offset:24
	global_load_dword v241, v[8:9], off offset:2072
	global_load_dword v242, v[10:11], off offset:24
	global_load_dword v243, v[16:17], off offset:24
	global_load_dword v244, v[20:21], off offset:3096
	global_load_dword v245, v[18:19], off offset:3096
	global_load_dword v246, v[22:23], off offset:1048
	global_load_dword v247, v[24:25], off offset:3096
	v_mov_b32_dpp v69, v126 row_ror:1 row_mask:0xf bank_mask:0xf
	v_mov_b32_dpp v83, v126 row_ror:2 row_mask:0xf bank_mask:0xf
	v_cndmask_b32_e64 v127, v69, 0, s[38:39]
	v_cndmask_b32_e64 v40, 0, v83, s[40:41]
	v_mov_b32_dpp v86, v128 row_ror:1 row_mask:0xf bank_mask:0xf
	v_cndmask_b32_e64 v129, v86, 0, s[38:39]
	v_mov_b32_dpp v87, v128 row_ror:2 row_mask:0xf bank_mask:0xf
	v_cndmask_b32_e64 v43, 0, v87, s[40:41]
	s_nop 0
	v_fma_f32 v84, v37, v40, v39
	v_pk_mul_f32 v[40:41], v[34:35], v[126:127]
	s_nop 0
	v_fma_f32 v43, v36, v43, v38
	v_add_f32_e32 v41, v41, v84
	v_add_f32_e32 v105, v40, v41
	v_mul_f32_e32 v40, 0xbfb8aa3b, v105
	v_exp_f32_e32 v111, v40
	v_mov_b32_e32 v41, v34
	s_nop 0
	v_pk_mul_f32 v[84:85], v[50:51], v[128:129]
	v_mov_b32_e32 v40, v50
	v_add_f32_e32 v34, 1.0, v111
	v_rcp_f32_e32 v50, v34
	v_add_f32_e32 v43, v85, v43
	v_add_f32_e32 v43, v84, v43
	v_mov_b32_e32 v34, v51
	v_mul_f32_e32 v50, v105, v50
	v_mul_f32_e32 v43, v43, v50
	v_mov_b32_dpp v101, v117 row_ror:2 row_mask:0xf bank_mask:0xf
	v_mov_b32_dpp v103, v116 row_ror:2 row_mask:0xf bank_mask:0xf
	v_mov_b32_dpp v100, v117 row_ror:1 row_mask:0xf bank_mask:0xf
	v_mov_b32_dpp v102, v116 row_ror:1 row_mask:0xf bank_mask:0xf
	v_cndmask_b32_e64 v85, v83, v101, s[40:41]
	v_cndmask_b32_e64 v84, v87, v103, s[40:41]
	v_cndmask_b32_e64 v51, v100, v69, s[38:39]
	v_cndmask_b32_e64 v50, v102, v86, s[38:39]
	v_pk_fma_f32 v[84:85], v[36:37], v[84:85], v[38:39]
	v_pk_fma_f32 v[50:51], v[34:35], v[50:51], v[84:85]
	s_nop 0
	v_pk_fma_f32 v[50:51], v[40:41], v[116:117], v[50:51]
	s_nop 0
	v_mul_f32_e32 v69, 0xbfb8aa3b, v51
	v_exp_f32_e32 v69, v69
	s_nop 0
	v_add_f32_e32 v69, 1.0, v69
	v_rcp_f32_e32 v69, v69
	s_nop 0
	v_mul_f32_e32 v51, v51, v69
	v_mul_f32_e32 v50, v50, v51
	v_mov_b32_dpp v105, v97 row_ror:2 row_mask:0xf bank_mask:0xf
	v_mov_b32_dpp v115, v96 row_ror:2 row_mask:0xf bank_mask:0xf
	v_mov_b32_dpp v83, v97 row_ror:1 row_mask:0xf bank_mask:0xf
	v_mov_b32_dpp v111, v96 row_ror:1 row_mask:0xf bank_mask:0xf
	v_cndmask_b32_e64 v87, v101, v105, s[40:41]
	v_cndmask_b32_e64 v86, v103, v115, s[40:41]
	v_cndmask_b32_e64 v85, v83, v100, s[38:39]
	v_cndmask_b32_e64 v84, v111, v102, s[38:39]
	v_pk_fma_f32 v[86:87], v[36:37], v[86:87], v[38:39]
	v_pk_fma_f32 v[84:85], v[34:35], v[84:85], v[86:87]
	v_pk_fma_f32 v[84:85], v[40:41], v[96:97], v[84:85]
	v_mul_f32_e32 v51, 0xbfb8aa3b, v85
	v_exp_f32_e32 v51, v51
	s_nop 0
	v_add_f32_e32 v51, 1.0, v51
	v_rcp_f32_e32 v51, v51
	s_nop 0
	v_mul_f32_e32 v51, v85, v51
	v_mul_f32_e32 v51, v84, v51
	v_mov_b32_dpp v97, v81 row_ror:2 row_mask:0xf bank_mask:0xf
	v_mov_b32_dpp v101, v80 row_ror:2 row_mask:0xf bank_mask:0xf
	v_mov_b32_dpp v96, v81 row_ror:1 row_mask:0xf bank_mask:0xf
	v_mov_b32_dpp v100, v80 row_ror:1 row_mask:0xf bank_mask:0xf
	v_cndmask_b32_e64 v87, v105, v97, s[40:41]
	v_cndmask_b32_e64 v86, v115, v101, s[40:41]
	v_cndmask_b32_e64 v85, v96, v83, s[38:39]
	v_cndmask_b32_e64 v84, v100, v111, s[38:39]
	v_pk_fma_f32 v[86:87], v[36:37], v[86:87], v[38:39]
	v_pk_fma_f32 v[84:85], v[34:35], v[84:85], v[86:87]
	v_pk_fma_f32 v[80:81], v[40:41], v[80:81], v[84:85]
	v_mul_f32_e32 v69, 0xbfb8aa3b, v81
	v_exp_f32_e32 v69, v69
	s_nop 0
	v_add_f32_e32 v69, 1.0, v69
	v_rcp_f32_e32 v69, v69
	s_nop 0
	v_mul_f32_e32 v69, v81, v69
	v_mul_f32_e32 v69, v80, v69
	v_mov_b32_dpp v86, v67 row_ror:2 row_mask:0xf bank_mask:0xf
	v_mov_b32_dpp v102, v66 row_ror:2 row_mask:0xf bank_mask:0xf
	v_mov_b32_dpp v83, v67 row_ror:1 row_mask:0xf bank_mask:0xf
	v_mov_b32_dpp v87, v66 row_ror:1 row_mask:0xf bank_mask:0xf
	v_cndmask_b32_e64 v85, v97, v86, s[40:41]
	v_cndmask_b32_e64 v84, v101, v102, s[40:41]
	v_cndmask_b32_e64 v81, v83, v96, s[38:39]
	v_cndmask_b32_e64 v80, v87, v100, s[38:39]
	v_pk_fma_f32 v[84:85], v[36:37], v[84:85], v[38:39]
	v_pk_fma_f32 v[80:81], v[34:35], v[80:81], v[84:85]
	v_pk_fma_f32 v[66:67], v[40:41], v[66:67], v[80:81]
	v_mul_f32_e32 v80, 0xbfb8aa3b, v67
	v_exp_f32_e32 v80, v80
	s_nop 0
	v_add_f32_e32 v80, 1.0, v80
	v_rcp_f32_e32 v80, v80
	s_nop 0
	v_mul_f32_e32 v67, v67, v80
	v_mul_f32_e32 v66, v66, v67
	v_mov_b32_dpp v97, v49 row_ror:2 row_mask:0xf bank_mask:0xf
	v_mov_b32_dpp v101, v48 row_ror:2 row_mask:0xf bank_mask:0xf
	v_mov_b32_dpp v96, v49 row_ror:1 row_mask:0xf bank_mask:0xf
	v_mov_b32_dpp v100, v48 row_ror:1 row_mask:0xf bank_mask:0xf
	v_cndmask_b32_e64 v85, v86, v97, s[40:41]
	v_cndmask_b32_e64 v84, v102, v101, s[40:41]
	v_cndmask_b32_e64 v81, v96, v83, s[38:39]
	v_cndmask_b32_e64 v80, v100, v87, s[38:39]
	v_pk_fma_f32 v[84:85], v[36:37], v[84:85], v[38:39]
	v_pk_fma_f32 v[80:81], v[34:35], v[80:81], v[84:85]
	v_pk_fma_f32 v[48:49], v[40:41], v[48:49], v[80:81]
	v_mul_f32_e32 v67, 0xbfb8aa3b, v49
	v_exp_f32_e32 v67, v67
	s_nop 0
	v_add_f32_e32 v67, 1.0, v67
	v_rcp_f32_e32 v67, v67
	s_nop 0
	v_mul_f32_e32 v49, v49, v67
	v_mul_f32_e32 v48, v48, v49
	v_mov_b32_dpp v86, v33 row_ror:2 row_mask:0xf bank_mask:0xf
	v_mov_b32_dpp v102, v32 row_ror:2 row_mask:0xf bank_mask:0xf
	v_mov_b32_dpp v83, v33 row_ror:1 row_mask:0xf bank_mask:0xf
	v_mov_b32_dpp v87, v32 row_ror:1 row_mask:0xf bank_mask:0xf
	v_cndmask_b32_e64 v85, v97, v86, s[40:41]
	v_cndmask_b32_e64 v84, v101, v102, s[40:41]
	v_cndmask_b32_e64 v81, v83, v96, s[38:39]
	v_cndmask_b32_e64 v80, v87, v100, s[38:39]
	v_pk_fma_f32 v[84:85], v[36:37], v[84:85], v[38:39]
	s_nop 0
	v_pk_fma_f32 v[80:81], v[34:35], v[80:81], v[84:85]
	v_pk_fma_f32 v[32:33], v[40:41], v[32:33], v[80:81]
	v_mul_f32_e32 v49, 0xbfb8aa3b, v33
	v_exp_f32_e32 v49, v49
	s_nop 0
	v_add_f32_e32 v49, 1.0, v49
	v_rcp_f32_e32 v49, v49
	s_nop 0
	v_mul_f32_e32 v33, v33, v49
	v_mul_f32_e32 v49, v32, v33
	v_mov_b32_dpp v80, v27 row_ror:2 row_mask:0xf bank_mask:0xf
	v_mov_b32_dpp v81, v26 row_ror:1 row_mask:0xf bank_mask:0xf
	v_mov_b32_dpp v84, v26 row_ror:2 row_mask:0xf bank_mask:0xf
	v_mov_b32_dpp v67, v27 row_ror:1 row_mask:0xf bank_mask:0xf
	v_cndmask_b32_e64 v32, v81, v87, s[38:39]
	v_cndmask_b32_e64 v81, v86, v80, s[40:41]
	v_cndmask_b32_e64 v80, v102, v84, s[40:41]
	v_cndmask_b32_e64 v33, v67, v83, s[38:39]
	v_pk_fma_f32 v[36:37], v[36:37], v[80:81], v[38:39]
	s_nop 0
	v_pk_fma_f32 v[32:33], v[34:35], v[32:33], v[36:37]
	s_nop 0
	v_pk_fma_f32 v[26:27], v[40:41], v[26:27], v[32:33]
	s_nop 0
	v_mul_f32_e32 v32, 0xbfb8aa3b, v27
	v_exp_f32_e32 v32, v32
	s_nop 0
	v_add_f32_e32 v32, 1.0, v32
	v_rcp_f32_e32 v32, v32
	s_nop 0
	v_mul_f32_e32 v27, v27, v32
	v_mul_f32_e32 v38, v26, v27
	s_waitcnt vmcnt(0)
; __device__ __forceinline__ float sigmoidf_(float x) { return __builtin_amdgcn_rcpf(1.0f + __expf(-x)); }
; template <int N> __device__ __forceinline__ float dpp_ror(float v) { return __builtin_bit_cast(float, __builtin_amdgcn_update_dpp(0, __builtin_bit_cast(int, v), 0x120 + N, 0xf, 0xf, false)); }
;     __device__ __forceinline__ void operator()(Acc& acc, const Unit& u, int wr, int wc, int fr, int fq) const {
;     ...
;         for (int n = 0; n < 2; ++n) {
; #pragma unroll
;             for (int i = 0; i < 4; ++i) {
;                 const int cg_ = ch0 + 4 * n + i, cv_ = DFF + cg_;
;                 const float g0 = cw[cg_], g1 = cw[NUP + cg_], g2 = cw[2 * NUP + cg_], gb = cb[cg_];
;                 const float v0 = cw[cv_], v1 = cw[NUP + cv_], v2 = cw[2 * NUP + cv_], vb = cb[cv_];
;                 float pg1 = 0.f, pg2 = 0.f, pv1 = 0.f, pv2 = 0.f;
; #pragma unroll
;                 for (int q = 0; q < 8; ++q) {
;                     float cgv = acc[q >> 2][0][q & 3][n][i], cvv = acc[q >> 2][1][q & 3][n][i];
;                     asm volatile("" : "+v"(cgv), "+v"(cvv) : "v"(chain));
;                     const float tg1 = dpp_ror<1>(cgv), tg2 = dpp_ror<2>(cgv), tv1 = dpp_ror<1>(cvv), tv2 = dpp_ror<2>(cvv);
;                     const float sg1 = fr >= 1 ? tg1 : pg1, sg2 = fr >= 2 ? tg2 : pg2, sv1 = fr >= 1 ? tv1 : pv1, sv2 = fr >= 2 ? tv2 : pv2;
;                     const float gg = gb + g0 * sg2 + g1 * sg1 + g2 * cgv;
;                     const float vv = vb + v0 * sv2 + v1 * sv1 + v2 * cvv;
;                     chain = gg * sigmoidf_(gg) * vv; acc[q >> 2][0][q & 3][n][i] = chain;
;                     pg1 = tg1; pg2 = tg2; pv1 = tv1; pv2 = tv2;
;                 }
;                 __builtin_amdgcn_sched_barrier(0);
;             }
;         }
	v_mov_b32_e32 v33, v240
	v_mov_b32_e32 v27, v241
	v_mov_b32_e32 v26, v242
	v_mov_b32_e32 v35, v243
	v_mov_b32_e32 v34, v244
	v_mov_b32_e32 v32, v245
	v_mov_b32_e32 v41, v246
	v_mov_b32_e32 v40, v247
	global_load_dword v232, v[6:7], off offset:28
	global_load_dword v233, v[8:9], off offset:2076
	global_load_dword v234, v[10:11], off offset:28
	global_load_dword v235, v[16:17], off offset:28
	global_load_dword v236, v[18:19], off offset:3100
	global_load_dword v237, v[22:23], off offset:1052
	global_load_dword v238, v[24:25], off offset:3100
	global_load_dword v239, v[20:21], off offset:3100
	v_mov_b32_dpp v67, v122 row_ror:1 row_mask:0xf bank_mask:0xf
	v_mov_b32_dpp v83, v122 row_ror:2 row_mask:0xf bank_mask:0xf
	v_cndmask_b32_e64 v123, v67, 0, s[38:39]
	v_cndmask_b32_e64 v36, 0, v83, s[40:41]
	v_mov_b32_dpp v84, v124 row_ror:1 row_mask:0xf bank_mask:0xf
	v_cndmask_b32_e64 v125, v84, 0, s[38:39]
	v_mov_b32_dpp v85, v124 row_ror:2 row_mask:0xf bank_mask:0xf
	v_cndmask_b32_e64 v39, 0, v85, s[40:41]
	s_nop 0
	v_fma_f32 v80, v33, v36, v35
	v_pk_mul_f32 v[36:37], v[26:27], v[122:123]
	s_nop 0
	v_fma_f32 v39, v32, v39, v34
	v_add_f32_e32 v37, v37, v80
	v_add_f32_e32 v100, v36, v37
	v_mul_f32_e32 v36, 0xbfb8aa3b, v100
	v_exp_f32_e32 v101, v36
	v_mov_b32_e32 v37, v26
	s_nop 0
	v_pk_mul_f32 v[80:81], v[40:41], v[124:125]
	v_mov_b32_e32 v36, v40
	v_add_f32_e32 v26, 1.0, v101
	v_rcp_f32_e32 v40, v26
	v_add_f32_e32 v39, v81, v39
	v_add_f32_e32 v39, v80, v39
	v_mov_b32_e32 v26, v41
	v_mul_f32_e32 v40, v100, v40
	v_mul_f32_e32 v39, v39, v40
	v_mov_b32_dpp v87, v113 row_ror:2 row_mask:0xf bank_mask:0xf
	v_mov_b32_dpp v97, v112 row_ror:2 row_mask:0xf bank_mask:0xf
	v_mov_b32_dpp v86, v113 row_ror:1 row_mask:0xf bank_mask:0xf
	v_mov_b32_dpp v96, v112 row_ror:1 row_mask:0xf bank_mask:0xf
	v_cndmask_b32_e64 v81, v83, v87, s[40:41]
	v_cndmask_b32_e64 v80, v85, v97, s[40:41]
	v_cndmask_b32_e64 v41, v86, v67, s[38:39]
	v_cndmask_b32_e64 v40, v96, v84, s[38:39]
	v_pk_fma_f32 v[80:81], v[32:33], v[80:81], v[34:35]
	v_pk_fma_f32 v[40:41], v[26:27], v[40:41], v[80:81]
	s_nop 0
	v_pk_fma_f32 v[40:41], v[36:37], v[112:113], v[40:41]
	s_nop 0
	v_mul_f32_e32 v67, 0xbfb8aa3b, v41
	v_exp_f32_e32 v67, v67
	s_nop 0
	v_add_f32_e32 v67, 1.0, v67
	v_rcp_f32_e32 v67, v67
	s_nop 0
	v_mul_f32_e32 v41, v41, v67
	v_mul_f32_e32 v40, v40, v41
	v_mov_b32_dpp v100, v95 row_ror:2 row_mask:0xf bank_mask:0xf
	v_mov_b32_dpp v102, v94 row_ror:2 row_mask:0xf bank_mask:0xf
	v_mov_b32_dpp v83, v95 row_ror:1 row_mask:0xf bank_mask:0xf
	v_mov_b32_dpp v101, v94 row_ror:1 row_mask:0xf bank_mask:0xf
	v_cndmask_b32_e64 v85, v87, v100, s[40:41]
	v_cndmask_b32_e64 v84, v97, v102, s[40:41]
	v_cndmask_b32_e64 v81, v83, v86, s[38:39]
	v_cndmask_b32_e64 v80, v101, v96, s[38:39]
	v_pk_fma_f32 v[84:85], v[32:33], v[84:85], v[34:35]
	v_pk_fma_f32 v[80:81], v[26:27], v[80:81], v[84:85]
	v_pk_fma_f32 v[80:81], v[36:37], v[94:95], v[80:81]
	v_mul_f32_e32 v41, 0xbfb8aa3b, v81
	v_exp_f32_e32 v41, v41
	s_nop 0
	v_add_f32_e32 v41, 1.0, v41
	v_rcp_f32_e32 v41, v41
	s_nop 0
	v_mul_f32_e32 v41, v81, v41
	v_mul_f32_e32 v41, v80, v41
	v_mov_b32_dpp v87, v79 row_ror:2 row_mask:0xf bank_mask:0xf
	v_mov_b32_dpp v95, v78 row_ror:2 row_mask:0xf bank_mask:0xf
	v_mov_b32_dpp v86, v79 row_ror:1 row_mask:0xf bank_mask:0xf
	v_mov_b32_dpp v94, v78 row_ror:1 row_mask:0xf bank_mask:0xf
	v_cndmask_b32_e64 v85, v100, v87, s[40:41]
	v_cndmask_b32_e64 v84, v102, v95, s[40:41]
	v_cndmask_b32_e64 v81, v86, v83, s[38:39]
	v_cndmask_b32_e64 v80, v94, v101, s[38:39]
	v_pk_fma_f32 v[84:85], v[32:33], v[84:85], v[34:35]
	v_pk_fma_f32 v[80:81], v[26:27], v[80:81], v[84:85]
	v_pk_fma_f32 v[78:79], v[36:37], v[78:79], v[80:81]
	v_mul_f32_e32 v67, 0xbfb8aa3b, v79
	v_exp_f32_e32 v67, v67
	s_nop 0
	v_add_f32_e32 v67, 1.0, v67
	v_rcp_f32_e32 v67, v67
	s_nop 0
	v_mul_f32_e32 v67, v79, v67
	v_mul_f32_e32 v67, v78, v67
	v_mov_b32_dpp v84, v65 row_ror:2 row_mask:0xf bank_mask:0xf
	v_mov_b32_dpp v96, v64 row_ror:2 row_mask:0xf bank_mask:0xf
	v_mov_b32_dpp v83, v65 row_ror:1 row_mask:0xf bank_mask:0xf
	v_mov_b32_dpp v85, v64 row_ror:1 row_mask:0xf bank_mask:0xf
	v_cndmask_b32_e64 v81, v87, v84, s[40:41]
	v_cndmask_b32_e64 v80, v95, v96, s[40:41]
	v_cndmask_b32_e64 v79, v83, v86, s[38:39]
	v_cndmask_b32_e64 v78, v85, v94, s[38:39]
	v_pk_fma_f32 v[80:81], v[32:33], v[80:81], v[34:35]
	v_pk_fma_f32 v[78:79], v[26:27], v[78:79], v[80:81]
	v_pk_fma_f32 v[64:65], v[36:37], v[64:65], v[78:79]
	v_mul_f32_e32 v78, 0xbfb8aa3b, v65
	v_exp_f32_e32 v78, v78
	s_nop 0
	v_add_f32_e32 v78, 1.0, v78
	v_rcp_f32_e32 v78, v78
	s_nop 0
	v_mul_f32_e32 v65, v65, v78
	v_mul_f32_e32 v64, v64, v65
	v_mov_b32_dpp v87, v47 row_ror:2 row_mask:0xf bank_mask:0xf
	v_mov_b32_dpp v95, v46 row_ror:2 row_mask:0xf bank_mask:0xf
	v_mov_b32_dpp v86, v47 row_ror:1 row_mask:0xf bank_mask:0xf
	v_mov_b32_dpp v94, v46 row_ror:1 row_mask:0xf bank_mask:0xf
	v_cndmask_b32_e64 v81, v84, v87, s[40:41]
	v_cndmask_b32_e64 v80, v96, v95, s[40:41]
	v_cndmask_b32_e64 v79, v86, v83, s[38:39]
	v_cndmask_b32_e64 v78, v94, v85, s[38:39]
	v_pk_fma_f32 v[80:81], v[32:33], v[80:81], v[34:35]
	v_pk_fma_f32 v[78:79], v[26:27], v[78:79], v[80:81]
	v_pk_fma_f32 v[46:47], v[36:37], v[46:47], v[78:79]
	v_mul_f32_e32 v65, 0xbfb8aa3b, v47
	v_exp_f32_e32 v65, v65
	s_nop 0
	v_add_f32_e32 v65, 1.0, v65
	v_rcp_f32_e32 v65, v65
	s_nop 0
	v_mul_f32_e32 v47, v47, v65
	v_mul_f32_e32 v46, v46, v47
	v_mov_b32_dpp v84, v31 row_ror:2 row_mask:0xf bank_mask:0xf
	v_mov_b32_dpp v96, v30 row_ror:2 row_mask:0xf bank_mask:0xf
	v_mov_b32_dpp v83, v31 row_ror:1 row_mask:0xf bank_mask:0xf
	v_mov_b32_dpp v85, v30 row_ror:1 row_mask:0xf bank_mask:0xf
	v_cndmask_b32_e64 v81, v87, v84, s[40:41]
	v_cndmask_b32_e64 v80, v95, v96, s[40:41]
	v_cndmask_b32_e64 v79, v83, v86, s[38:39]
	v_cndmask_b32_e64 v78, v85, v94, s[38:39]
	v_pk_fma_f32 v[80:81], v[32:33], v[80:81], v[34:35]
	v_pk_fma_f32 v[78:79], v[26:27], v[78:79], v[80:81]
	v_pk_fma_f32 v[30:31], v[36:37], v[30:31], v[78:79]
	v_mul_f32_e32 v47, 0xbfb8aa3b, v31
	v_exp_f32_e32 v47, v47
	s_nop 0
	v_add_f32_e32 v47, 1.0, v47
	v_rcp_f32_e32 v47, v47
	s_nop 0
	v_mul_f32_e32 v31, v31, v47
	v_mul_f32_e32 v30, v30, v31
	v_mov_b32_dpp v80, v15 row_ror:2 row_mask:0xf bank_mask:0xf
	v_mov_b32_dpp v86, v14 row_ror:2 row_mask:0xf bank_mask:0xf
	v_mov_b32_dpp v65, v15 row_ror:1 row_mask:0xf bank_mask:0xf
	v_mov_b32_dpp v78, v14 row_ror:1 row_mask:0xf bank_mask:0xf
	v_cndmask_b32_e64 v81, v84, v80, s[40:41]
	v_cndmask_b32_e64 v80, v96, v86, s[40:41]
	v_cndmask_b32_e64 v79, v65, v83, s[38:39]
	v_cndmask_b32_e64 v78, v78, v85, s[38:39]
	v_pk_fma_f32 v[32:33], v[32:33], v[80:81], v[34:35]
	s_nop 0
	v_pk_fma_f32 v[26:27], v[26:27], v[78:79], v[32:33]
	s_nop 0
	v_pk_fma_f32 v[14:15], v[36:37], v[14:15], v[26:27]
	s_nop 0
	v_mul_f32_e32 v26, 0xbfb8aa3b, v15
	v_exp_f32_e32 v26, v26
	s_nop 0
	v_add_f32_e32 v26, 1.0, v26
	v_rcp_f32_e32 v26, v26
	s_nop 0
	v_mul_f32_e32 v15, v15, v26
	v_mul_f32_e32 v26, v14, v15
	s_waitcnt vmcnt(0)
; __device__ __forceinline__ unsigned pk2(float lo, float hi) { const f32x2_t v = {lo, hi}; const bf16x2_t b = __builtin_convertvector(v, bf16x2_t); return __builtin_bit_cast(unsigned, b); }
; __device__ __forceinline__ float sigmoidf_(float x) { return __builtin_amdgcn_rcpf(1.0f + __expf(-x)); }
;     __device__ __forceinline__ void operator()(Acc& acc, const Unit& u, int wr, int wc, int fr, int fq) const {
;     ...
;         for (int n = 0; n < 2; ++n) {
; #pragma unroll
;             for (int i = 0; i < 4; ++i) {
;                 const int cg_ = ch0 + 4 * n + i, cv_ = DFF + cg_;
;                 const float g0 = cw[cg_], g1 = cw[NUP + cg_], g2 = cw[2 * NUP + cg_], gb = cb[cg_];
;                 const float v0 = cw[cv_], v1 = cw[NUP + cv_], v2 = cw[2 * NUP + cv_], vb = cb[cv_];
;                 float pg1 = 0.f, pg2 = 0.f, pv1 = 0.f, pv2 = 0.f;
; #pragma unroll
;                 for (int q = 0; q < 8; ++q) {
;                     float cgv = acc[q >> 2][0][q & 3][n][i], cvv = acc[q >> 2][1][q & 3][n][i];
;                     asm volatile("" : "+v"(cgv), "+v"(cvv) : "v"(chain));
;                     const float tg1 = dpp_ror<1>(cgv), tg2 = dpp_ror<2>(cgv), tv1 = dpp_ror<1>(cvv), tv2 = dpp_ror<2>(cvv);
;                     const float sg1 = fr >= 1 ? tg1 : pg1, sg2 = fr >= 2 ? tg2 : pg2, sv1 = fr >= 1 ? tv1 : pv1, sv2 = fr >= 2 ? tv2 : pv2;
;                     const float gg = gb + g0 * sg2 + g1 * sg1 + g2 * cgv;
;                     const float vv = vb + v0 * sv2 + v1 * sv1 + v2 * cvv;
;                     chain = gg * sigmoidf_(gg) * vv; acc[q >> 2][0][q & 3][n][i] = chain;
;                     pg1 = tg1; pg2 = tg2; pv1 = tv1; pv2 = tv2;
;                 }
;                 __builtin_amdgcn_sched_barrier(0);
;             }
;         }
; #pragma unroll
;         for (int q = 0; q < 8; ++q) {
;             const int t = tbase + 16 * q;
;             if ((16 * q + fr >= 2) && (t < SEQ)) {
;                 const f32x4 a0 = acc[q >> 2][0][q & 3][0], a1 = acc[q >> 2][0][q & 3][1];
;                 u32x4 w; w.x = pk2(a0[0], a0[1]); w.y = pk2(a0[2], a0[3]); w.z = pk2(a1[0], a1[1]); w.w = pk2(a1[2], a1[3]);
;                 *(u32x4*)(act + (size_t)(b * SEQ + t) * DFF + ch0) = w;
	v_mov_b32_e32 v15, v232
	s_nop 0
	v_mov_b32_e32 v7, v233
	v_mov_b32_e32 v6, v234
	s_nop 0
	v_mov_b32_e32 v9, v235
	v_mov_b32_e32 v14, v236
	s_nop 0
	v_mov_b32_e32 v17, v237
	v_mov_b32_e32 v16, v238
	v_mov_b32_e32 v8, v239
	v_mov_b32_dpp v19, v120 row_ror:1 row_mask:0xf bank_mask:0xf
	v_mov_b32_dpp v22, v120 row_ror:2 row_mask:0xf bank_mask:0xf
	v_cndmask_b32_e64 v121, v19, 0, s[38:39]
	v_cndmask_b32_e64 v10, 0, v22, s[40:41]
	v_mov_b32_dpp v20, v110 row_ror:1 row_mask:0xf bank_mask:0xf
	v_mov_b32_dpp v24, v110 row_ror:2 row_mask:0xf bank_mask:0xf
	v_cndmask_b32_e64 v111, v20, 0, s[38:39]
	v_cndmask_b32_e64 v18, 0, v24, s[40:41]
	v_mov_b32_e32 v35, v3
	v_mov_b32_e32 v36, v3
	s_nop 0
	v_fma_f32 v21, v15, v10, v9
	v_pk_mul_f32 v[10:11], v[6:7], v[120:121]
	s_nop 0
	v_fma_f32 v18, v14, v18, v8
	v_add_f32_e32 v11, v11, v21
	v_add_f32_e32 v21, v10, v11
	v_pk_mul_f32 v[10:11], v[16:17], v[110:111]
	s_nop 0
	v_add_f32_e32 v11, v11, v18
	v_add_f32_e32 v10, v10, v11
	v_mul_f32_e32 v11, 0xbfb8aa3b, v21
	v_exp_f32_e32 v11, v11
	s_nop 0
	v_add_f32_e32 v11, 1.0, v11
	v_rcp_f32_e32 v11, v11
	s_nop 0
	v_mul_f32_e32 v11, v21, v11
	v_mul_f32_e32 v18, v10, v11
	v_mov_b32_e32 v11, v6
	v_mov_b32_e32 v6, v17
	v_mov_b32_dpp v27, v109 row_ror:2 row_mask:0xf bank_mask:0xf
	v_mov_b32_dpp v32, v108 row_ror:2 row_mask:0xf bank_mask:0xf
	v_mov_b32_dpp v25, v109 row_ror:1 row_mask:0xf bank_mask:0xf
	v_mov_b32_dpp v31, v108 row_ror:1 row_mask:0xf bank_mask:0xf
	v_cndmask_b32_e64 v23, v22, v27, s[40:41]
	v_cndmask_b32_e64 v22, v24, v32, s[40:41]
	v_cndmask_b32_e64 v21, v25, v19, s[38:39]
	v_cndmask_b32_e64 v20, v31, v20, s[38:39]
	v_pk_fma_f32 v[22:23], v[14:15], v[22:23], v[8:9]
	v_mov_b32_e32 v10, v16
	v_pk_fma_f32 v[16:17], v[6:7], v[20:21], v[22:23]
	v_pk_fma_f32 v[16:17], v[10:11], v[108:109], v[16:17]
	s_nop 0
	v_mul_f32_e32 v19, 0xbfb8aa3b, v17
	v_exp_f32_e32 v19, v19
	s_nop 0
	v_add_f32_e32 v19, 1.0, v19
	v_rcp_f32_e32 v19, v19
	s_nop 0
	v_mul_f32_e32 v17, v17, v19
	v_mul_f32_e32 v16, v16, v17
	v_mov_b32_dpp v24, v93 row_ror:2 row_mask:0xf bank_mask:0xf
	v_mov_b32_dpp v34, v92 row_ror:2 row_mask:0xf bank_mask:0xf
	v_mov_b32_dpp v19, v93 row_ror:1 row_mask:0xf bank_mask:0xf
	v_mov_b32_dpp v33, v92 row_ror:1 row_mask:0xf bank_mask:0xf
	v_cndmask_b32_e64 v23, v27, v24, s[40:41]
	v_cndmask_b32_e64 v22, v32, v34, s[40:41]
	v_cndmask_b32_e64 v21, v19, v25, s[38:39]
	v_cndmask_b32_e64 v20, v33, v31, s[38:39]
	v_pk_fma_f32 v[22:23], v[14:15], v[22:23], v[8:9]
	v_pk_fma_f32 v[20:21], v[6:7], v[20:21], v[22:23]
	v_pk_fma_f32 v[20:21], v[10:11], v[92:93], v[20:21]
	v_mul_f32_e32 v17, 0xbfb8aa3b, v21
	v_exp_f32_e32 v17, v17
	s_nop 0
	v_add_f32_e32 v17, 1.0, v17
	v_rcp_f32_e32 v17, v17
	s_nop 0
	v_mul_f32_e32 v17, v21, v17
	v_mul_f32_e32 v17, v20, v17
	v_mov_b32_dpp v27, v77 row_ror:2 row_mask:0xf bank_mask:0xf
	v_mov_b32_dpp v32, v76 row_ror:2 row_mask:0xf bank_mask:0xf
	v_mov_b32_dpp v25, v77 row_ror:1 row_mask:0xf bank_mask:0xf
	v_mov_b32_dpp v31, v76 row_ror:1 row_mask:0xf bank_mask:0xf
	v_cndmask_b32_e64 v23, v24, v27, s[40:41]
	v_cndmask_b32_e64 v22, v34, v32, s[40:41]
	v_cndmask_b32_e64 v21, v25, v19, s[38:39]
	v_cndmask_b32_e64 v20, v31, v33, s[38:39]
	v_pk_fma_f32 v[22:23], v[14:15], v[22:23], v[8:9]
	v_pk_fma_f32 v[20:21], v[6:7], v[20:21], v[22:23]
	v_pk_fma_f32 v[20:21], v[10:11], v[76:77], v[20:21]
	v_mul_f32_e32 v19, 0xbfb8aa3b, v21
	v_exp_f32_e32 v19, v19
	s_nop 0
	v_add_f32_e32 v19, 1.0, v19
	v_rcp_f32_e32 v19, v19
	s_nop 0
	v_mul_f32_e32 v19, v21, v19
	v_mul_f32_e32 v19, v20, v19
	v_mov_b32_dpp v33, v61 row_ror:2 row_mask:0xf bank_mask:0xf
	v_mov_b32_dpp v35, v60 row_ror:2 row_mask:0xf bank_mask:0xf
	v_mov_b32_dpp v24, v61 row_ror:1 row_mask:0xf bank_mask:0xf
	v_mov_b32_dpp v34, v60 row_ror:1 row_mask:0xf bank_mask:0xf
	v_cndmask_b32_e64 v23, v27, v33, s[40:41]
	v_cndmask_b32_e64 v22, v32, v35, s[40:41]
	v_cndmask_b32_e64 v21, v24, v25, s[38:39]
	v_cndmask_b32_e64 v20, v34, v31, s[38:39]
	v_pk_fma_f32 v[22:23], v[14:15], v[22:23], v[8:9]
	v_pk_fma_f32 v[20:21], v[6:7], v[20:21], v[22:23]
	v_pk_fma_f32 v[20:21], v[10:11], v[60:61], v[20:21]
	v_mul_f32_e32 v22, 0xbfb8aa3b, v21
	v_exp_f32_e32 v22, v22
	s_nop 0
	v_add_f32_e32 v22, 1.0, v22
	v_rcp_f32_e32 v22, v22
	s_nop 0
	v_mul_f32_e32 v21, v21, v22
	v_mul_f32_e32 v20, v20, v21
	v_mov_b32_dpp v27, v45 row_ror:1 row_mask:0xf bank_mask:0xf
	v_mov_b32_dpp v31, v45 row_ror:2 row_mask:0xf bank_mask:0xf
	v_mov_b32_dpp v36, v44 row_ror:2 row_mask:0xf bank_mask:0xf
	v_mov_b32_dpp v32, v44 row_ror:1 row_mask:0xf bank_mask:0xf
	v_cndmask_b32_e64 v23, v27, v24, s[38:39]
	v_cndmask_b32_e64 v25, v33, v31, s[40:41]
	v_cndmask_b32_e64 v24, v35, v36, s[40:41]
	v_cndmask_b32_e64 v22, v32, v34, s[38:39]
	v_pk_fma_f32 v[24:25], v[14:15], v[24:25], v[8:9]
	s_nop 0
	v_pk_fma_f32 v[22:23], v[6:7], v[22:23], v[24:25]
	v_pk_fma_f32 v[22:23], v[10:11], v[44:45], v[22:23]
	s_nop 0
	v_mul_f32_e32 v21, 0xbfb8aa3b, v23
	v_exp_f32_e32 v21, v21
	s_nop 0
	v_add_f32_e32 v21, 1.0, v21
	v_rcp_f32_e32 v21, v21
	s_nop 0
	v_mul_f32_e32 v21, v23, v21
	v_mul_f32_e32 v24, v22, v21
	v_mov_b32_dpp v22, v29 row_ror:2 row_mask:0xf bank_mask:0xf
	v_mov_b32_dpp v25, v28 row_ror:2 row_mask:0xf bank_mask:0xf
	v_mov_b32_dpp v21, v29 row_ror:1 row_mask:0xf bank_mask:0xf
	v_mov_b32_dpp v23, v28 row_ror:1 row_mask:0xf bank_mask:0xf
	v_cndmask_b32_e64 v35, v31, v22, s[40:41]
	v_cndmask_b32_e64 v34, v36, v25, s[40:41]
	v_cndmask_b32_e64 v33, v21, v27, s[38:39]
	v_cndmask_b32_e64 v32, v23, v32, s[38:39]
	v_pk_fma_f32 v[34:35], v[14:15], v[34:35], v[8:9]
	v_pk_fma_f32 v[32:33], v[6:7], v[32:33], v[34:35]
	s_nop 0
	v_pk_fma_f32 v[28:29], v[10:11], v[28:29], v[32:33]
	v_mul_f32_e32 v27, 0xbfb8aa3b, v29
	v_exp_f32_e32 v27, v27
	s_nop 0
	v_add_f32_e32 v27, 1.0, v27
	v_rcp_f32_e32 v27, v27
	s_nop 0
	v_mul_f32_e32 v27, v29, v27
	v_mul_f32_e32 v27, v28, v27
	s_nop 0
	v_mov_b32_dpp v28, v13 row_ror:1 row_mask:0xf bank_mask:0xf
	v_mov_b32_dpp v29, v13 row_ror:2 row_mask:0xf bank_mask:0xf
	v_mov_b32_dpp v31, v12 row_ror:1 row_mask:0xf bank_mask:0xf
	v_mov_b32_dpp v32, v12 row_ror:2 row_mask:0xf bank_mask:0xf
	v_cmp_gt_i32_e32 vcc, s97, v198
	s_and_b64 s[44:45], s[40:41], vcc
	s_and_saveexec_b64 s[34:35], s[44:45]
	s_cbranch_execz .LBB0_45
	v_cvt_pk_bf16_f32 v37, v39, v18
	v_add_u32_e32 v18, s20, v198
	v_mov_b64_e32 v[44:45], s[8:9]
	s_movk_i32 s21, 0x1600
	v_mad_i64_i32 v[44:45], s[44:45], v18, s21, v[44:45]
	v_cvt_pk_bf16_f32 v34, v184, v137
	v_cvt_pk_bf16_f32 v35, v99, v63
	v_cvt_pk_bf16_f32 v36, v56, v43
	v_lshl_add_u64 v[44:45], v[4:5], 1, v[44:45]
	flat_store_dwordx4 v[44:45], v[34:37]
